# v101 + s_setprio 1 hoisted above the pre-MMA barrier and duplicate lgkmcnt(0) dropped at 36 K-loop sites
# speedup vs baseline: 1.0025x; 1.0016x over previous
.LBB0_333:
	s_add_u32 s68, s56, s49
	s_addc_u32 s70, s57, 0
	s_add_u32 s64, s68, 0x100
	s_addc_u32 s65, s70, 0
	s_and_b64 s[62:63], s[60:61], exec
	s_cselect_b32 s65, s18, s65
	s_cselect_b32 s64, s19, s64
	s_add_u32 s49, s54, s49
	s_addc_u32 s62, s55, 0
	s_add_u32 s49, s49, 0x100
	s_addc_u32 s62, s62, 0
	s_add_i32 s80, 0, 0x10000
	s_and_b64 s[60:61], s[60:61], exec
	s_cselect_b32 s67, s33, s62
	s_cselect_b32 s66, s45, s49
	s_add_i32 s61, 0, 0x14000
	s_add_u32 s72, s68, 0x10080
	s_addc_u32 s73, s70, 0
	s_add_i32 s79, s80, s2
	s_add_i32 m0, s4, 0xc000
	s_add_i32 s82, s4, 0xe000
	s_add_i32 s76, s79, 0x2000
	s_add_u32 s70, s66, 0x10000
	v_add_u32_e32 v152, s80, v138
	v_add_u32_e32 v168, s61, v138
	s_addc_u32 s71, s67, 0
	s_add_i32 s78, s61, s2
	ds_read_b128 v[140:143], v152
	ds_read_b128 v[144:147], v152 offset:1024
	ds_read_b128 v[148:151], v152 offset:2048
	ds_read_b128 v[152:155], v152 offset:3072
	ds_read_b128 v[156:159], v168
	ds_read_b128 v[160:163], v168 offset:1024
	ds_read_b128 v[164:167], v168 offset:2048
	ds_read_b128 v[168:171], v168 offset:3072
	s_add_i32 s77, s78, 0x2000
	s_add_i32 s75, 0, 0x18000
	s_add_i32 s74, 0, 0x1c000
	s_add_u32 s62, s64, 0x10000
	s_addc_u32 s63, s65, 0
	s_add_i32 s68, s75, s2
	s_add_i32 s49, s68, 0x2000
	s_add_u32 s60, s66, 0x10080
	s_addc_u32 s61, s67, 0
	s_add_i32 s81, s74, s2
	s_add_i32 s80, s81, 0x2000
	v_lshl_add_u64 v[204:205], s[72:73], 0, v[136:137]
	ds_read_b128 v[172:175], v139
	ds_read_b128 v[176:179], v139 offset:1024
	ds_read_b128 v[180:183], v139 offset:2048
	ds_read_b128 v[184:187], v139 offset:3072
	ds_read_b128 v[188:191], v139 offset:4096
	ds_read_b128 v[192:195], v139 offset:5120
	ds_read_b128 v[196:199], v139 offset:6144
	ds_read_b128 v[214:217], v139 offset:7168
	global_load_lds_dwordx4 v[204:205], off
	v_lshl_add_u64 v[204:205], s[72:73], 0, v[134:135]
	s_mov_b32 m0, s82
	s_nop 0
	global_load_lds_dwordx4 v[204:205], off
	s_waitcnt vmcnt(8)
	s_waitcnt lgkmcnt(0)
	s_setprio 1
	s_barrier
	v_mfma_f32_16x16x32_bf16 v[128:131], v[140:143], v[172:175], v[128:131]
	v_mfma_f32_16x16x32_bf16 v[124:127], v[148:151], v[172:175], v[124:127]
	v_mfma_f32_16x16x32_bf16 v[120:123], v[140:143], v[180:183], v[120:123]
	v_mfma_f32_16x16x32_bf16 v[116:119], v[148:151], v[180:183], v[116:119]
	v_mfma_f32_16x16x32_bf16 v[104:107], v[140:143], v[188:191], v[104:107]
	v_mfma_f32_16x16x32_bf16 v[100:103], v[148:151], v[188:191], v[100:103]
	v_mfma_f32_16x16x32_bf16 v[86:89], v[140:143], v[196:199], v[86:89]
	v_mfma_f32_16x16x32_bf16 v[82:85], v[148:151], v[196:199], v[82:85]
	v_mfma_f32_16x16x32_bf16 v[128:131], v[144:147], v[176:179], v[128:131]
	v_mfma_f32_16x16x32_bf16 v[124:127], v[152:155], v[176:179], v[124:127]
	v_mfma_f32_16x16x32_bf16 v[120:123], v[144:147], v[184:187], v[120:123]
	v_mfma_f32_16x16x32_bf16 v[116:119], v[152:155], v[184:187], v[116:119]
	v_mfma_f32_16x16x32_bf16 v[104:107], v[144:147], v[192:195], v[104:107]
	v_mfma_f32_16x16x32_bf16 v[100:103], v[152:155], v[192:195], v[100:103]
	v_mfma_f32_16x16x32_bf16 v[86:89], v[144:147], v[214:217], v[86:89]
	v_mfma_f32_16x16x32_bf16 v[82:85], v[152:155], v[214:217], v[82:85]
	s_setprio 0
	s_setprio 1
	v_mfma_f32_16x16x32_bf16 v[112:115], v[156:159], v[172:175], v[112:115]
	v_mfma_f32_16x16x32_bf16 v[108:111], v[164:167], v[172:175], v[108:111]
	v_mfma_f32_16x16x32_bf16 v[94:97], v[156:159], v[180:183], v[94:97]
	v_mfma_f32_16x16x32_bf16 v[90:93], v[164:167], v[180:183], v[90:93]
	v_mfma_f32_16x16x32_bf16 v[78:81], v[156:159], v[188:191], v[78:81]
	v_mfma_f32_16x16x32_bf16 v[74:77], v[164:167], v[188:191], v[74:77]
	v_mfma_f32_16x16x32_bf16 v[70:73], v[156:159], v[196:199], v[70:73]
	v_mfma_f32_16x16x32_bf16 v[66:69], v[164:167], v[196:199], v[66:69]
	v_mfma_f32_16x16x32_bf16 v[112:115], v[160:163], v[176:179], v[112:115]
	v_mfma_f32_16x16x32_bf16 v[108:111], v[168:171], v[176:179], v[108:111]
	v_mfma_f32_16x16x32_bf16 v[94:97], v[160:163], v[184:187], v[94:97]
	v_mfma_f32_16x16x32_bf16 v[90:93], v[168:171], v[184:187], v[90:93]
	v_mfma_f32_16x16x32_bf16 v[78:81], v[160:163], v[192:195], v[78:81]
	v_mfma_f32_16x16x32_bf16 v[74:77], v[168:171], v[192:195], v[74:77]
	v_mfma_f32_16x16x32_bf16 v[70:73], v[160:163], v[214:217], v[70:73]
	v_mfma_f32_16x16x32_bf16 v[66:69], v[168:171], v[214:217], v[66:69]
	s_setprio 0
	s_barrier
	s_mov_b32 m0, s79
	v_lshl_add_u64 v[204:205], s[66:67], 0, v[98:99]
	ds_read_b128 v[172:175], v139 offset:16384
	ds_read_b128 v[176:179], v139 offset:17408
	ds_read_b128 v[180:183], v139 offset:18432
	ds_read_b128 v[184:187], v139 offset:19456
	ds_read_b128 v[188:191], v139 offset:20480
	ds_read_b128 v[192:195], v139 offset:21504
	ds_read_b128 v[196:199], v139 offset:22528
	ds_read_b128 v[214:217], v139 offset:23552
	global_load_lds_dwordx4 v[204:205], off
	v_lshl_add_u64 v[206:207], s[66:67], 0, v[132:133]
	s_mov_b32 m0, s76
	v_lshl_add_u64 v[208:209], s[70:71], 0, v[98:99]
	global_load_lds_dwordx4 v[206:207], off
	s_mov_b32 m0, s78
	v_lshl_add_u64 v[210:211], s[64:65], 0, v[134:135]
	global_load_lds_dwordx4 v[208:209], off
	v_lshl_add_u64 v[208:209], s[70:71], 0, v[132:133]
	s_mov_b32 m0, s77
	s_nop 0
	global_load_lds_dwordx4 v[208:209], off
	v_lshl_add_u64 v[208:209], s[64:65], 0, v[136:137]
	s_mov_b32 m0, s4
	s_nop 0
	global_load_lds_dwordx4 v[208:209], off
	s_mov_b32 m0, s7
	s_nop 0
	global_load_lds_dwordx4 v[210:211], off
	s_waitcnt vmcnt(8)
	s_waitcnt lgkmcnt(0)
	s_setprio 1
	s_barrier
	v_mfma_f32_16x16x32_bf16 v[62:65], v[140:143], v[172:175], v[62:65]
	v_mfma_f32_16x16x32_bf16 v[58:61], v[148:151], v[172:175], v[58:61]
	v_mfma_f32_16x16x32_bf16 v[54:57], v[140:143], v[180:183], v[54:57]
	v_mfma_f32_16x16x32_bf16 v[50:53], v[148:151], v[180:183], v[50:53]
	v_mfma_f32_16x16x32_bf16 v[38:41], v[140:143], v[188:191], v[38:41]
	v_mfma_f32_16x16x32_bf16 v[34:37], v[148:151], v[188:191], v[34:37]
	v_mfma_f32_16x16x32_bf16 v[22:25], v[140:143], v[196:199], v[22:25]
	v_mfma_f32_16x16x32_bf16 v[18:21], v[148:151], v[196:199], v[18:21]
	v_mfma_f32_16x16x32_bf16 v[62:65], v[144:147], v[176:179], v[62:65]
	v_mfma_f32_16x16x32_bf16 v[58:61], v[152:155], v[176:179], v[58:61]
	v_mfma_f32_16x16x32_bf16 v[54:57], v[144:147], v[184:187], v[54:57]
	v_mfma_f32_16x16x32_bf16 v[50:53], v[152:155], v[184:187], v[50:53]
	v_mfma_f32_16x16x32_bf16 v[38:41], v[144:147], v[192:195], v[38:41]
	v_mfma_f32_16x16x32_bf16 v[34:37], v[152:155], v[192:195], v[34:37]
	v_mfma_f32_16x16x32_bf16 v[22:25], v[144:147], v[214:217], v[22:25]
	v_mfma_f32_16x16x32_bf16 v[18:21], v[152:155], v[214:217], v[18:21]
	s_setprio 0
	s_setprio 1
	v_mfma_f32_16x16x32_bf16 v[46:49], v[156:159], v[172:175], v[46:49]
	v_mfma_f32_16x16x32_bf16 v[42:45], v[164:167], v[172:175], v[42:45]
	v_mfma_f32_16x16x32_bf16 v[30:33], v[156:159], v[180:183], v[30:33]
	v_mfma_f32_16x16x32_bf16 v[26:29], v[164:167], v[180:183], v[26:29]
	v_mfma_f32_16x16x32_bf16 v[14:17], v[156:159], v[188:191], v[14:17]
	v_mfma_f32_16x16x32_bf16 v[10:13], v[164:167], v[188:191], v[10:13]
	v_mfma_f32_16x16x32_bf16 v[6:9], v[156:159], v[196:199], v[6:9]
	v_mfma_f32_16x16x32_bf16 v[2:5], v[164:167], v[196:199], v[2:5]
	v_mfma_f32_16x16x32_bf16 v[46:49], v[160:163], v[176:179], v[46:49]
	v_mfma_f32_16x16x32_bf16 v[42:45], v[168:171], v[176:179], v[42:45]
	v_mfma_f32_16x16x32_bf16 v[30:33], v[160:163], v[184:187], v[30:33]
	v_mfma_f32_16x16x32_bf16 v[26:29], v[168:171], v[184:187], v[26:29]
	v_mfma_f32_16x16x32_bf16 v[14:17], v[160:163], v[192:195], v[14:17]
	v_mfma_f32_16x16x32_bf16 v[10:13], v[168:171], v[192:195], v[10:13]
	v_mfma_f32_16x16x32_bf16 v[6:9], v[160:163], v[214:217], v[6:9]
	v_mfma_f32_16x16x32_bf16 v[2:5], v[168:171], v[214:217], v[2:5]
	s_setprio 0
	s_barrier
	v_add_u32_e32 v152, s75, v138
	v_add_u32_e32 v168, s74, v138
	ds_read_b128 v[140:143], v152
	ds_read_b128 v[144:147], v152 offset:1024
	ds_read_b128 v[148:151], v152 offset:2048
	ds_read_b128 v[152:155], v152 offset:3072
	ds_read_b128 v[156:159], v168
	ds_read_b128 v[160:163], v168 offset:1024
	ds_read_b128 v[164:167], v168 offset:2048
	ds_read_b128 v[168:171], v168 offset:3072
	s_mov_b32 m0, s8
	v_lshl_add_u64 v[218:219], s[62:63], 0, v[136:137]
	ds_read_b128 v[172:175], v139 offset:32768
	ds_read_b128 v[176:179], v139 offset:33792
	ds_read_b128 v[180:183], v139 offset:34816
	ds_read_b128 v[184:187], v139 offset:35840
	ds_read_b128 v[188:191], v139 offset:36864
	ds_read_b128 v[192:195], v139 offset:37888
	ds_read_b128 v[196:199], v139 offset:38912
	ds_read_b128 v[214:217], v139 offset:39936
	global_load_lds_dwordx4 v[218:219], off
	v_lshl_add_u64 v[218:219], s[62:63], 0, v[134:135]
	s_mov_b32 m0, s9
	s_nop 0
	global_load_lds_dwordx4 v[218:219], off
	s_waitcnt vmcnt(8)
	s_waitcnt lgkmcnt(0)
	s_setprio 1
	s_barrier
	v_mfma_f32_16x16x32_bf16 v[128:131], v[140:143], v[172:175], v[128:131]
	v_mfma_f32_16x16x32_bf16 v[124:127], v[148:151], v[172:175], v[124:127]
	v_mfma_f32_16x16x32_bf16 v[120:123], v[140:143], v[180:183], v[120:123]
	v_mfma_f32_16x16x32_bf16 v[116:119], v[148:151], v[180:183], v[116:119]
	v_mfma_f32_16x16x32_bf16 v[104:107], v[140:143], v[188:191], v[104:107]
	v_mfma_f32_16x16x32_bf16 v[100:103], v[148:151], v[188:191], v[100:103]
	v_mfma_f32_16x16x32_bf16 v[86:89], v[140:143], v[196:199], v[86:89]
	v_mfma_f32_16x16x32_bf16 v[82:85], v[148:151], v[196:199], v[82:85]
	v_mfma_f32_16x16x32_bf16 v[128:131], v[144:147], v[176:179], v[128:131]
	v_mfma_f32_16x16x32_bf16 v[124:127], v[152:155], v[176:179], v[124:127]
	v_mfma_f32_16x16x32_bf16 v[120:123], v[144:147], v[184:187], v[120:123]
	v_mfma_f32_16x16x32_bf16 v[116:119], v[152:155], v[184:187], v[116:119]
	v_mfma_f32_16x16x32_bf16 v[104:107], v[144:147], v[192:195], v[104:107]
	v_mfma_f32_16x16x32_bf16 v[100:103], v[152:155], v[192:195], v[100:103]
	v_mfma_f32_16x16x32_bf16 v[86:89], v[144:147], v[214:217], v[86:89]
	v_mfma_f32_16x16x32_bf16 v[82:85], v[152:155], v[214:217], v[82:85]
	s_setprio 0
	s_setprio 1
	v_mfma_f32_16x16x32_bf16 v[112:115], v[156:159], v[172:175], v[112:115]
	v_mfma_f32_16x16x32_bf16 v[108:111], v[164:167], v[172:175], v[108:111]
	v_mfma_f32_16x16x32_bf16 v[94:97], v[156:159], v[180:183], v[94:97]
	v_mfma_f32_16x16x32_bf16 v[90:93], v[164:167], v[180:183], v[90:93]
	v_mfma_f32_16x16x32_bf16 v[78:81], v[156:159], v[188:191], v[78:81]
	v_mfma_f32_16x16x32_bf16 v[74:77], v[164:167], v[188:191], v[74:77]
	v_mfma_f32_16x16x32_bf16 v[70:73], v[156:159], v[196:199], v[70:73]
	v_mfma_f32_16x16x32_bf16 v[66:69], v[164:167], v[196:199], v[66:69]
	v_mfma_f32_16x16x32_bf16 v[112:115], v[160:163], v[176:179], v[112:115]
	v_mfma_f32_16x16x32_bf16 v[108:111], v[168:171], v[176:179], v[108:111]
	v_mfma_f32_16x16x32_bf16 v[94:97], v[160:163], v[184:187], v[94:97]
	v_mfma_f32_16x16x32_bf16 v[90:93], v[168:171], v[184:187], v[90:93]
	v_mfma_f32_16x16x32_bf16 v[78:81], v[160:163], v[192:195], v[78:81]
	v_mfma_f32_16x16x32_bf16 v[74:77], v[168:171], v[192:195], v[74:77]
	v_mfma_f32_16x16x32_bf16 v[70:73], v[160:163], v[214:217], v[70:73]
	v_mfma_f32_16x16x32_bf16 v[66:69], v[168:171], v[214:217], v[66:69]
	s_setprio 0
	s_barrier
	s_mov_b32 m0, s68
	v_lshl_add_u64 v[204:205], v[204:205], 0, s[28:29]
	ds_read_b128 v[172:175], v139 offset:49152
	ds_read_b128 v[176:179], v139 offset:50176
	ds_read_b128 v[180:183], v139 offset:51200
	ds_read_b128 v[184:187], v139 offset:52224
	ds_read_b128 v[188:191], v139 offset:53248
	ds_read_b128 v[192:195], v139 offset:54272
	ds_read_b128 v[196:199], v139 offset:55296
	ds_read_b128 v[214:217], v139 offset:56320
	global_load_lds_dwordx4 v[204:205], off
	v_lshl_add_u64 v[204:205], v[206:207], 0, s[28:29]
	s_mov_b32 m0, s49
	s_nop 0
	global_load_lds_dwordx4 v[204:205], off
	v_lshl_add_u64 v[204:205], s[60:61], 0, v[98:99]
	s_mov_b32 m0, s81
	s_nop 0
	global_load_lds_dwordx4 v[204:205], off
	v_lshl_add_u64 v[204:205], s[60:61], 0, v[132:133]
	s_mov_b32 m0, s80
	s_nop 0
	global_load_lds_dwordx4 v[204:205], off
	v_lshl_add_u64 v[204:205], v[208:209], 0, s[28:29]
	s_mov_b32 m0, s10
	s_nop 0
	global_load_lds_dwordx4 v[204:205], off
	v_lshl_add_u64 v[204:205], v[210:211], 0, s[28:29]
	s_mov_b32 m0, s11
	s_nop 0
	global_load_lds_dwordx4 v[204:205], off
	s_waitcnt vmcnt(8)
	s_waitcnt lgkmcnt(0)
	s_setprio 1
	s_barrier
	v_mfma_f32_16x16x32_bf16 v[62:65], v[140:143], v[172:175], v[62:65]
	v_mfma_f32_16x16x32_bf16 v[58:61], v[148:151], v[172:175], v[58:61]
	v_mfma_f32_16x16x32_bf16 v[54:57], v[140:143], v[180:183], v[54:57]
	v_mfma_f32_16x16x32_bf16 v[50:53], v[148:151], v[180:183], v[50:53]
	v_mfma_f32_16x16x32_bf16 v[38:41], v[140:143], v[188:191], v[38:41]
	v_mfma_f32_16x16x32_bf16 v[34:37], v[148:151], v[188:191], v[34:37]
	v_mfma_f32_16x16x32_bf16 v[22:25], v[140:143], v[196:199], v[22:25]
	v_mfma_f32_16x16x32_bf16 v[18:21], v[148:151], v[196:199], v[18:21]
	v_mfma_f32_16x16x32_bf16 v[62:65], v[144:147], v[176:179], v[62:65]
	v_mfma_f32_16x16x32_bf16 v[58:61], v[152:155], v[176:179], v[58:61]
	v_mfma_f32_16x16x32_bf16 v[54:57], v[144:147], v[184:187], v[54:57]
	v_mfma_f32_16x16x32_bf16 v[50:53], v[152:155], v[184:187], v[50:53]
	v_mfma_f32_16x16x32_bf16 v[38:41], v[144:147], v[192:195], v[38:41]
	v_mfma_f32_16x16x32_bf16 v[34:37], v[152:155], v[192:195], v[34:37]
	v_mfma_f32_16x16x32_bf16 v[22:25], v[144:147], v[214:217], v[22:25]
	v_mfma_f32_16x16x32_bf16 v[18:21], v[152:155], v[214:217], v[18:21]
	s_setprio 0
	s_setprio 1
	v_mfma_f32_16x16x32_bf16 v[46:49], v[156:159], v[172:175], v[46:49]
	v_mfma_f32_16x16x32_bf16 v[42:45], v[164:167], v[172:175], v[42:45]
	v_mfma_f32_16x16x32_bf16 v[30:33], v[156:159], v[180:183], v[30:33]
	v_mfma_f32_16x16x32_bf16 v[26:29], v[164:167], v[180:183], v[26:29]
	v_mfma_f32_16x16x32_bf16 v[14:17], v[156:159], v[188:191], v[14:17]
	v_mfma_f32_16x16x32_bf16 v[10:13], v[164:167], v[188:191], v[10:13]
	v_mfma_f32_16x16x32_bf16 v[6:9], v[156:159], v[196:199], v[6:9]
	v_mfma_f32_16x16x32_bf16 v[2:5], v[164:167], v[196:199], v[2:5]
	v_mfma_f32_16x16x32_bf16 v[46:49], v[160:163], v[176:179], v[46:49]
	v_mfma_f32_16x16x32_bf16 v[42:45], v[168:171], v[176:179], v[42:45]
	v_mfma_f32_16x16x32_bf16 v[30:33], v[160:163], v[184:187], v[30:33]
	v_mfma_f32_16x16x32_bf16 v[26:29], v[168:171], v[184:187], v[26:29]
	v_mfma_f32_16x16x32_bf16 v[14:17], v[160:163], v[192:195], v[14:17]
	v_mfma_f32_16x16x32_bf16 v[10:13], v[168:171], v[192:195], v[10:13]
	v_mfma_f32_16x16x32_bf16 v[6:9], v[160:163], v[214:217], v[6:9]
	v_mfma_f32_16x16x32_bf16 v[2:5], v[168:171], v[214:217], v[2:5]
	s_setprio 0
	s_barrier
	s_movk_i32 s49, 0x100
	s_andn2_b64 vcc, exec, s[58:59]
	s_mov_b64 s[60:61], -1
	s_mov_b64 s[58:59], 0
	s_cbranch_vccz .LBB0_333
	s_and_b64 vcc, exec, s[40:41]
	s_cbranch_vccz .LBB0_336
	s_barrier

.LBB0_438:
	s_add_u32 s42, s40, 0xfffc0080
	s_addc_u32 s43, s41, -1
	s_add_i32 s67, 0, 0x10000
	s_cmp_eq_u32 s66, 12
	s_cselect_b32 s45, s1, s43
	s_cselect_b32 s44, s49, s42
	s_cselect_b32 s43, s55, s65
	s_cselect_b32 s42, s63, s64
	s_add_i32 s72, 0, 0x14000
	v_add_u32_e32 v108, s67, v162
	v_add_u32_e32 v160, s72, v162
	ds_read_b128 v[90:93], v108
	ds_read_b128 v[94:97], v108 offset:1024
	ds_read_b128 v[100:103], v108 offset:2048
	ds_read_b128 v[108:111], v108 offset:3072
	ds_read_b128 v[166:169], v160
	ds_read_b128 v[170:173], v160 offset:1024
	ds_read_b128 v[174:177], v160 offset:2048
	ds_read_b128 v[178:181], v160 offset:3072
	v_lshl_add_u64 v[160:161], s[40:41], 0, v[156:157]
	s_add_i32 m0, s8, 0xc000
	ds_read_b128 v[182:185], v163
	ds_read_b128 v[186:189], v163 offset:1024
	ds_read_b128 v[190:193], v163 offset:2048
	ds_read_b128 v[194:197], v163 offset:3072
	ds_read_b128 v[214:217], v163 offset:4096
	ds_read_b128 v[218:221], v163 offset:5120
	ds_read_b128 v[222:225], v163 offset:6144
	ds_read_b128 v[226:229], v163 offset:7168
	global_load_lds_dwordx4 v[160:161], off
	v_lshl_add_u64 v[160:161], s[40:41], 0, v[158:159]
	s_add_i32 m0, s8, 0xe000
	s_nop 0
	global_load_lds_dwordx4 v[160:161], off
	s_waitcnt vmcnt(8)
	s_waitcnt lgkmcnt(0)
	s_setprio 1
	s_barrier
	v_mfma_f32_16x16x32_bf16 v[144:147], v[90:93], v[182:185], v[144:147]
	v_mfma_f32_16x16x32_bf16 v[140:143], v[100:103], v[182:185], v[140:143]
	v_mfma_f32_16x16x32_bf16 v[128:131], v[90:93], v[190:193], v[128:131]
	v_mfma_f32_16x16x32_bf16 v[124:127], v[100:103], v[190:193], v[124:127]
	v_mfma_f32_16x16x32_bf16 v[112:115], v[90:93], v[214:217], v[112:115]
	v_mfma_f32_16x16x32_bf16 v[104:107], v[100:103], v[214:217], v[104:107]
	v_mfma_f32_16x16x32_bf16 v[78:81], v[90:93], v[222:225], v[78:81]
	v_mfma_f32_16x16x32_bf16 v[74:77], v[100:103], v[222:225], v[74:77]
	v_mfma_f32_16x16x32_bf16 v[144:147], v[94:97], v[186:189], v[144:147]
	v_mfma_f32_16x16x32_bf16 v[140:143], v[108:111], v[186:189], v[140:143]
	v_mfma_f32_16x16x32_bf16 v[128:131], v[94:97], v[194:197], v[128:131]
	v_mfma_f32_16x16x32_bf16 v[124:127], v[108:111], v[194:197], v[124:127]
	v_mfma_f32_16x16x32_bf16 v[112:115], v[94:97], v[218:221], v[112:115]
	v_mfma_f32_16x16x32_bf16 v[104:107], v[108:111], v[218:221], v[104:107]
	v_mfma_f32_16x16x32_bf16 v[78:81], v[94:97], v[226:229], v[78:81]
	v_mfma_f32_16x16x32_bf16 v[74:77], v[108:111], v[226:229], v[74:77]
	s_setprio 0
	s_setprio 1
	v_mfma_f32_16x16x32_bf16 v[136:139], v[166:169], v[182:185], v[136:139]
	v_mfma_f32_16x16x32_bf16 v[132:135], v[174:177], v[182:185], v[132:135]
	v_mfma_f32_16x16x32_bf16 v[120:123], v[166:169], v[190:193], v[120:123]
	v_mfma_f32_16x16x32_bf16 v[116:119], v[174:177], v[190:193], v[116:119]
	v_mfma_f32_16x16x32_bf16 v[86:89], v[166:169], v[214:217], v[86:89]
	v_mfma_f32_16x16x32_bf16 v[82:85], v[174:177], v[214:217], v[82:85]
	v_mfma_f32_16x16x32_bf16 v[70:73], v[166:169], v[222:225], v[70:73]
	v_mfma_f32_16x16x32_bf16 v[66:69], v[174:177], v[222:225], v[66:69]
	v_mfma_f32_16x16x32_bf16 v[136:139], v[170:173], v[186:189], v[136:139]
	v_mfma_f32_16x16x32_bf16 v[132:135], v[178:181], v[186:189], v[132:135]
	v_mfma_f32_16x16x32_bf16 v[120:123], v[170:173], v[194:197], v[120:123]
	v_mfma_f32_16x16x32_bf16 v[116:119], v[178:181], v[194:197], v[116:119]
	v_mfma_f32_16x16x32_bf16 v[86:89], v[170:173], v[218:221], v[86:89]
	v_mfma_f32_16x16x32_bf16 v[82:85], v[178:181], v[218:221], v[82:85]
	v_mfma_f32_16x16x32_bf16 v[70:73], v[170:173], v[226:229], v[70:73]
	v_mfma_f32_16x16x32_bf16 v[66:69], v[178:181], v[226:229], v[66:69]
	s_setprio 0
	s_barrier
	s_add_i32 s67, s67, s7
	v_lshl_add_u64 v[160:161], s[42:43], 0, v[98:99]
	s_mov_b32 m0, s67
	ds_read_b128 v[182:185], v163 offset:16384
	ds_read_b128 v[186:189], v163 offset:17408
	ds_read_b128 v[190:193], v163 offset:18432
	ds_read_b128 v[194:197], v163 offset:19456
	ds_read_b128 v[214:217], v163 offset:20480
	ds_read_b128 v[218:221], v163 offset:21504
	ds_read_b128 v[222:225], v163 offset:22528
	ds_read_b128 v[226:229], v163 offset:23552
	global_load_lds_dwordx4 v[160:161], off
	s_add_i32 m0, s67, 0x2000
	s_add_u32 s70, s42, 0x40000
	v_lshl_add_u64 v[198:199], s[42:43], 0, v[152:153]
	s_addc_u32 s71, s43, 0
	s_add_i32 s67, s72, s7
	global_load_lds_dwordx4 v[198:199], off
	v_lshl_add_u64 v[204:205], s[70:71], 0, v[98:99]
	s_mov_b32 m0, s67
	v_lshl_add_u64 v[206:207], s[44:45], 0, v[150:151]
	global_load_lds_dwordx4 v[204:205], off
	v_lshl_add_u64 v[204:205], s[70:71], 0, v[152:153]
	s_add_i32 m0, s67, 0x2000
	s_nop 0
	global_load_lds_dwordx4 v[204:205], off
	v_lshl_add_u64 v[204:205], s[44:45], 0, v[148:149]
	s_mov_b32 m0, s8
	s_nop 0
	global_load_lds_dwordx4 v[204:205], off
	s_mov_b32 m0, s9
	s_nop 0
	global_load_lds_dwordx4 v[206:207], off
	s_waitcnt vmcnt(8)
	s_waitcnt lgkmcnt(0)
	s_setprio 1
	s_barrier
	v_mfma_f32_16x16x32_bf16 v[62:65], v[90:93], v[182:185], v[62:65]
	v_mfma_f32_16x16x32_bf16 v[58:61], v[100:103], v[182:185], v[58:61]
	v_mfma_f32_16x16x32_bf16 v[46:49], v[90:93], v[190:193], v[46:49]
	v_mfma_f32_16x16x32_bf16 v[42:45], v[100:103], v[190:193], v[42:45]
	v_mfma_f32_16x16x32_bf16 v[30:33], v[90:93], v[214:217], v[30:33]
	v_mfma_f32_16x16x32_bf16 v[26:29], v[100:103], v[214:217], v[26:29]
	v_mfma_f32_16x16x32_bf16 v[14:17], v[90:93], v[222:225], v[14:17]
	v_mfma_f32_16x16x32_bf16 v[10:13], v[100:103], v[222:225], v[10:13]
	v_mfma_f32_16x16x32_bf16 v[62:65], v[94:97], v[186:189], v[62:65]
	v_mfma_f32_16x16x32_bf16 v[58:61], v[108:111], v[186:189], v[58:61]
	v_mfma_f32_16x16x32_bf16 v[46:49], v[94:97], v[194:197], v[46:49]
	v_mfma_f32_16x16x32_bf16 v[42:45], v[108:111], v[194:197], v[42:45]
	v_mfma_f32_16x16x32_bf16 v[30:33], v[94:97], v[218:221], v[30:33]
	v_mfma_f32_16x16x32_bf16 v[26:29], v[108:111], v[218:221], v[26:29]
	v_mfma_f32_16x16x32_bf16 v[14:17], v[94:97], v[226:229], v[14:17]
	v_mfma_f32_16x16x32_bf16 v[10:13], v[108:111], v[226:229], v[10:13]
	s_setprio 0
	s_setprio 1
	v_mfma_f32_16x16x32_bf16 v[54:57], v[166:169], v[182:185], v[54:57]
	v_mfma_f32_16x16x32_bf16 v[50:53], v[174:177], v[182:185], v[50:53]
	v_mfma_f32_16x16x32_bf16 v[38:41], v[166:169], v[190:193], v[38:41]
	v_mfma_f32_16x16x32_bf16 v[34:37], v[174:177], v[190:193], v[34:37]
	v_mfma_f32_16x16x32_bf16 v[22:25], v[166:169], v[214:217], v[22:25]
	v_mfma_f32_16x16x32_bf16 v[18:21], v[174:177], v[214:217], v[18:21]
	v_mfma_f32_16x16x32_bf16 v[6:9], v[166:169], v[222:225], v[6:9]
	v_mfma_f32_16x16x32_bf16 v[2:5], v[174:177], v[222:225], v[2:5]
	v_mfma_f32_16x16x32_bf16 v[54:57], v[170:173], v[186:189], v[54:57]
	v_mfma_f32_16x16x32_bf16 v[50:53], v[178:181], v[186:189], v[50:53]
	v_mfma_f32_16x16x32_bf16 v[38:41], v[170:173], v[194:197], v[38:41]
	v_mfma_f32_16x16x32_bf16 v[34:37], v[178:181], v[194:197], v[34:37]
	v_mfma_f32_16x16x32_bf16 v[22:25], v[170:173], v[218:221], v[22:25]
	v_mfma_f32_16x16x32_bf16 v[18:21], v[178:181], v[218:221], v[18:21]
	v_mfma_f32_16x16x32_bf16 v[6:9], v[170:173], v[226:229], v[6:9]
	v_mfma_f32_16x16x32_bf16 v[2:5], v[178:181], v[226:229], v[2:5]
	s_setprio 0
	s_barrier
	s_add_i32 s67, 0, 0x18000
	s_add_i32 s70, 0, 0x1c000
	v_add_u32_e32 v108, s67, v162
	v_add_u32_e32 v165, s70, v162
	ds_read_b128 v[90:93], v108
	ds_read_b128 v[94:97], v108 offset:1024
	ds_read_b128 v[100:103], v108 offset:2048
	ds_read_b128 v[108:111], v108 offset:3072
	ds_read_b128 v[166:169], v165
	ds_read_b128 v[170:173], v165 offset:1024
	ds_read_b128 v[174:177], v165 offset:2048
	ds_read_b128 v[178:181], v165 offset:3072
	s_add_u32 s44, s44, 0x40000
	s_addc_u32 s45, s45, 0
	s_mov_b32 m0, s10
	v_lshl_add_u64 v[208:209], s[44:45], 0, v[148:149]
	ds_read_b128 v[182:185], v163 offset:32768
	ds_read_b128 v[186:189], v163 offset:33792
	ds_read_b128 v[190:193], v163 offset:34816
	ds_read_b128 v[194:197], v163 offset:35840
	ds_read_b128 v[214:217], v163 offset:36864
	ds_read_b128 v[218:221], v163 offset:37888
	ds_read_b128 v[222:225], v163 offset:38912
	ds_read_b128 v[226:229], v163 offset:39936
	global_load_lds_dwordx4 v[208:209], off
	v_lshl_add_u64 v[208:209], s[44:45], 0, v[150:151]
	s_mov_b32 m0, s11
	s_nop 0
	global_load_lds_dwordx4 v[208:209], off
	s_waitcnt vmcnt(8)
	s_waitcnt lgkmcnt(0)
	s_setprio 1
	s_barrier
	v_mfma_f32_16x16x32_bf16 v[144:147], v[90:93], v[182:185], v[144:147]
	v_mfma_f32_16x16x32_bf16 v[140:143], v[100:103], v[182:185], v[140:143]
	v_mfma_f32_16x16x32_bf16 v[128:131], v[90:93], v[190:193], v[128:131]
	v_mfma_f32_16x16x32_bf16 v[124:127], v[100:103], v[190:193], v[124:127]
	v_mfma_f32_16x16x32_bf16 v[112:115], v[90:93], v[214:217], v[112:115]
	v_mfma_f32_16x16x32_bf16 v[104:107], v[100:103], v[214:217], v[104:107]
	v_mfma_f32_16x16x32_bf16 v[78:81], v[90:93], v[222:225], v[78:81]
	v_mfma_f32_16x16x32_bf16 v[74:77], v[100:103], v[222:225], v[74:77]
	v_mfma_f32_16x16x32_bf16 v[144:147], v[94:97], v[186:189], v[144:147]
	v_mfma_f32_16x16x32_bf16 v[140:143], v[108:111], v[186:189], v[140:143]
	v_mfma_f32_16x16x32_bf16 v[128:131], v[94:97], v[194:197], v[128:131]
	v_mfma_f32_16x16x32_bf16 v[124:127], v[108:111], v[194:197], v[124:127]
	v_mfma_f32_16x16x32_bf16 v[112:115], v[94:97], v[218:221], v[112:115]
	v_mfma_f32_16x16x32_bf16 v[104:107], v[108:111], v[218:221], v[104:107]
	v_mfma_f32_16x16x32_bf16 v[78:81], v[94:97], v[226:229], v[78:81]
	v_mfma_f32_16x16x32_bf16 v[74:77], v[108:111], v[226:229], v[74:77]
	s_setprio 0
	s_setprio 1
	v_mfma_f32_16x16x32_bf16 v[136:139], v[166:169], v[182:185], v[136:139]
	v_mfma_f32_16x16x32_bf16 v[132:135], v[174:177], v[182:185], v[132:135]
	v_mfma_f32_16x16x32_bf16 v[120:123], v[166:169], v[190:193], v[120:123]
	v_mfma_f32_16x16x32_bf16 v[116:119], v[174:177], v[190:193], v[116:119]
	v_mfma_f32_16x16x32_bf16 v[86:89], v[166:169], v[214:217], v[86:89]
	v_mfma_f32_16x16x32_bf16 v[82:85], v[174:177], v[214:217], v[82:85]
	v_mfma_f32_16x16x32_bf16 v[70:73], v[166:169], v[222:225], v[70:73]
	v_mfma_f32_16x16x32_bf16 v[66:69], v[174:177], v[222:225], v[66:69]
	v_mfma_f32_16x16x32_bf16 v[136:139], v[170:173], v[186:189], v[136:139]
	v_mfma_f32_16x16x32_bf16 v[132:135], v[178:181], v[186:189], v[132:135]
	v_mfma_f32_16x16x32_bf16 v[120:123], v[170:173], v[194:197], v[120:123]
	v_mfma_f32_16x16x32_bf16 v[116:119], v[178:181], v[194:197], v[116:119]
	v_mfma_f32_16x16x32_bf16 v[86:89], v[170:173], v[218:221], v[86:89]
	v_mfma_f32_16x16x32_bf16 v[82:85], v[178:181], v[218:221], v[82:85]
	v_mfma_f32_16x16x32_bf16 v[70:73], v[170:173], v[226:229], v[70:73]
	v_mfma_f32_16x16x32_bf16 v[66:69], v[178:181], v[226:229], v[66:69]
	s_setprio 0
	s_barrier
	s_add_i32 s44, s67, s7
	v_lshl_add_u64 v[160:161], v[160:161], 0, s[28:29]
	s_mov_b32 m0, s44
	ds_read_b128 v[182:185], v163 offset:49152
	ds_read_b128 v[186:189], v163 offset:50176
	ds_read_b128 v[190:193], v163 offset:51200
	ds_read_b128 v[194:197], v163 offset:52224
	ds_read_b128 v[214:217], v163 offset:53248
	ds_read_b128 v[218:221], v163 offset:54272
	ds_read_b128 v[222:225], v163 offset:55296
	ds_read_b128 v[226:229], v163 offset:56320
	global_load_lds_dwordx4 v[160:161], off
	s_add_i32 m0, s44, 0x2000
	s_add_u32 s42, s42, 0x40080
	v_lshl_add_u64 v[160:161], v[198:199], 0, s[28:29]
	s_addc_u32 s43, s43, 0
	s_add_i32 s44, s70, s7
	global_load_lds_dwordx4 v[160:161], off
	v_lshl_add_u64 v[160:161], s[42:43], 0, v[98:99]
	s_mov_b32 m0, s44
	s_nop 0
	global_load_lds_dwordx4 v[160:161], off
	v_lshl_add_u64 v[160:161], s[42:43], 0, v[152:153]
	s_add_i32 m0, s44, 0x2000
	s_nop 0
	global_load_lds_dwordx4 v[160:161], off
	v_lshl_add_u64 v[160:161], v[204:205], 0, s[28:29]
	s_mov_b32 m0, s16
	s_nop 0
	global_load_lds_dwordx4 v[160:161], off
	v_lshl_add_u64 v[160:161], v[206:207], 0, s[28:29]
	s_mov_b32 m0, s17
	s_nop 0
	global_load_lds_dwordx4 v[160:161], off
	s_waitcnt vmcnt(8)
	s_waitcnt lgkmcnt(0)
	s_setprio 1
	s_barrier
	v_mfma_f32_16x16x32_bf16 v[62:65], v[90:93], v[182:185], v[62:65]
	v_mfma_f32_16x16x32_bf16 v[58:61], v[100:103], v[182:185], v[58:61]
	v_mfma_f32_16x16x32_bf16 v[46:49], v[90:93], v[190:193], v[46:49]
	v_mfma_f32_16x16x32_bf16 v[42:45], v[100:103], v[190:193], v[42:45]
	v_mfma_f32_16x16x32_bf16 v[30:33], v[90:93], v[214:217], v[30:33]
	v_mfma_f32_16x16x32_bf16 v[26:29], v[100:103], v[214:217], v[26:29]
	v_mfma_f32_16x16x32_bf16 v[14:17], v[90:93], v[222:225], v[14:17]
	v_mfma_f32_16x16x32_bf16 v[10:13], v[100:103], v[222:225], v[10:13]
	v_mfma_f32_16x16x32_bf16 v[62:65], v[94:97], v[186:189], v[62:65]
	v_mfma_f32_16x16x32_bf16 v[58:61], v[108:111], v[186:189], v[58:61]
	v_mfma_f32_16x16x32_bf16 v[46:49], v[94:97], v[194:197], v[46:49]
	v_mfma_f32_16x16x32_bf16 v[42:45], v[108:111], v[194:197], v[42:45]
	v_mfma_f32_16x16x32_bf16 v[30:33], v[94:97], v[218:221], v[30:33]
	v_mfma_f32_16x16x32_bf16 v[26:29], v[108:111], v[218:221], v[26:29]
	v_mfma_f32_16x16x32_bf16 v[14:17], v[94:97], v[226:229], v[14:17]
	v_mfma_f32_16x16x32_bf16 v[10:13], v[108:111], v[226:229], v[10:13]
	s_setprio 0
	s_setprio 1
	v_mfma_f32_16x16x32_bf16 v[54:57], v[166:169], v[182:185], v[54:57]
	v_mfma_f32_16x16x32_bf16 v[50:53], v[174:177], v[182:185], v[50:53]
	v_mfma_f32_16x16x32_bf16 v[38:41], v[166:169], v[190:193], v[38:41]
	v_mfma_f32_16x16x32_bf16 v[34:37], v[174:177], v[190:193], v[34:37]
	v_mfma_f32_16x16x32_bf16 v[22:25], v[166:169], v[214:217], v[22:25]
	v_mfma_f32_16x16x32_bf16 v[18:21], v[174:177], v[214:217], v[18:21]
	v_mfma_f32_16x16x32_bf16 v[6:9], v[166:169], v[222:225], v[6:9]
	v_mfma_f32_16x16x32_bf16 v[2:5], v[174:177], v[222:225], v[2:5]
	v_mfma_f32_16x16x32_bf16 v[54:57], v[170:173], v[186:189], v[54:57]
	v_mfma_f32_16x16x32_bf16 v[50:53], v[178:181], v[186:189], v[50:53]
	v_mfma_f32_16x16x32_bf16 v[38:41], v[170:173], v[194:197], v[38:41]
	v_mfma_f32_16x16x32_bf16 v[34:37], v[178:181], v[194:197], v[34:37]
	v_mfma_f32_16x16x32_bf16 v[22:25], v[170:173], v[218:221], v[22:25]
	v_mfma_f32_16x16x32_bf16 v[18:21], v[178:181], v[218:221], v[18:21]
	v_mfma_f32_16x16x32_bf16 v[6:9], v[170:173], v[226:229], v[6:9]
	v_mfma_f32_16x16x32_bf16 v[2:5], v[178:181], v[226:229], v[2:5]
	s_setprio 0
	s_barrier
	s_add_i32 s66, s66, 2
	s_add_u32 s40, s40, 0x100
	s_addc_u32 s41, s41, 0
	s_add_u32 s64, s64, 0x100
	s_addc_u32 s65, s65, 0
	s_cmp_gt_u32 s66, 13
	s_cbranch_scc0 .LBB0_438
	s_and_b64 vcc, exec, s[22:23]
	s_cbranch_vccz .LBB0_441
	s_barrier

.LBB0_647:
	s_add_i32 s68, s42, 2
	s_add_u32 s43, s40, 0xfff80080
	s_addc_u32 s54, s41, -1
	s_add_i32 s70, 0, 0x10000
	s_cmp_eq_u32 s65, s42
	s_cselect_b32 s55, s49, s54
	s_cselect_b32 s54, s63, s43
	v_add_u32_e32 v146, s70, v149
	s_cselect_b32 s43, s51, s67
	s_cselect_b32 s42, s50, s66
	s_add_i32 s72, 0, 0x14000
	ds_read_b128 v[152:155], v146
	ds_read_b128 v[156:159], v146 offset:1024
	ds_read_b128 v[160:163], v146 offset:2048
	ds_read_b128 v[164:167], v146 offset:3072
	v_add_u32_e32 v146, s72, v149
	ds_read_b128 v[168:171], v146
	ds_read_b128 v[172:175], v146 offset:1024
	ds_read_b128 v[176:179], v146 offset:2048
	ds_read_b128 v[180:183], v146 offset:3072
	v_lshl_add_u64 v[146:147], s[40:41], 0, v[142:143]
	s_add_i32 m0, s11, 0xc000
	ds_read_b128 v[184:187], v150
	ds_read_b128 v[188:191], v150 offset:1024
	ds_read_b128 v[192:195], v150 offset:2048
	ds_read_b128 v[196:199], v150 offset:3072
	ds_read_b128 v[214:217], v150 offset:4096
	ds_read_b128 v[218:221], v150 offset:5120
	ds_read_b128 v[222:225], v150 offset:6144
	ds_read_b128 v[226:229], v150 offset:7168
	global_load_lds_dwordx4 v[146:147], off
	v_lshl_add_u64 v[146:147], s[40:41], 0, v[144:145]
	s_add_i32 m0, s11, 0xe000
	s_nop 0
	global_load_lds_dwordx4 v[146:147], off
	s_waitcnt vmcnt(8)
	s_waitcnt lgkmcnt(0)
	s_setprio 1
	s_barrier
	v_mfma_f32_16x16x32_bf16 v[128:131], v[152:155], v[184:187], v[128:131]
	v_mfma_f32_16x16x32_bf16 v[124:127], v[160:163], v[184:187], v[124:127]
	v_mfma_f32_16x16x32_bf16 v[112:115], v[152:155], v[192:195], v[112:115]
	v_mfma_f32_16x16x32_bf16 v[108:111], v[160:163], v[192:195], v[108:111]
	v_mfma_f32_16x16x32_bf16 v[94:97], v[152:155], v[214:217], v[94:97]
	v_mfma_f32_16x16x32_bf16 v[90:93], v[160:163], v[214:217], v[90:93]
	v_mfma_f32_16x16x32_bf16 v[78:81], v[152:155], v[222:225], v[78:81]
	v_mfma_f32_16x16x32_bf16 v[74:77], v[160:163], v[222:225], v[74:77]
	v_mfma_f32_16x16x32_bf16 v[128:131], v[156:159], v[188:191], v[128:131]
	v_mfma_f32_16x16x32_bf16 v[124:127], v[164:167], v[188:191], v[124:127]
	v_mfma_f32_16x16x32_bf16 v[112:115], v[156:159], v[196:199], v[112:115]
	v_mfma_f32_16x16x32_bf16 v[108:111], v[164:167], v[196:199], v[108:111]
	v_mfma_f32_16x16x32_bf16 v[94:97], v[156:159], v[218:221], v[94:97]
	v_mfma_f32_16x16x32_bf16 v[90:93], v[164:167], v[218:221], v[90:93]
	v_mfma_f32_16x16x32_bf16 v[78:81], v[156:159], v[226:229], v[78:81]
	v_mfma_f32_16x16x32_bf16 v[74:77], v[164:167], v[226:229], v[74:77]
	s_setprio 0
	s_setprio 1
	v_mfma_f32_16x16x32_bf16 v[120:123], v[168:171], v[184:187], v[120:123]
	v_mfma_f32_16x16x32_bf16 v[116:119], v[176:179], v[184:187], v[116:119]
	v_mfma_f32_16x16x32_bf16 v[104:107], v[168:171], v[192:195], v[104:107]
	v_mfma_f32_16x16x32_bf16 v[100:103], v[176:179], v[192:195], v[100:103]
	v_mfma_f32_16x16x32_bf16 v[86:89], v[168:171], v[214:217], v[86:89]
	v_mfma_f32_16x16x32_bf16 v[82:85], v[176:179], v[214:217], v[82:85]
	v_mfma_f32_16x16x32_bf16 v[70:73], v[168:171], v[222:225], v[70:73]
	v_mfma_f32_16x16x32_bf16 v[66:69], v[176:179], v[222:225], v[66:69]
	v_mfma_f32_16x16x32_bf16 v[120:123], v[172:175], v[188:191], v[120:123]
	v_mfma_f32_16x16x32_bf16 v[116:119], v[180:183], v[188:191], v[116:119]
	v_mfma_f32_16x16x32_bf16 v[104:107], v[172:175], v[196:199], v[104:107]
	v_mfma_f32_16x16x32_bf16 v[100:103], v[180:183], v[196:199], v[100:103]
	v_mfma_f32_16x16x32_bf16 v[86:89], v[172:175], v[218:221], v[86:89]
	v_mfma_f32_16x16x32_bf16 v[82:85], v[180:183], v[218:221], v[82:85]
	v_mfma_f32_16x16x32_bf16 v[70:73], v[172:175], v[226:229], v[70:73]
	v_mfma_f32_16x16x32_bf16 v[66:69], v[180:183], v[226:229], v[66:69]
	s_setprio 0
	s_barrier
	s_add_i32 s70, s70, s10
	v_lshl_add_u64 v[146:147], s[42:43], 0, v[98:99]
	s_mov_b32 m0, s70
	ds_read_b128 v[184:187], v150 offset:16384
	ds_read_b128 v[188:191], v150 offset:17408
	ds_read_b128 v[192:195], v150 offset:18432
	ds_read_b128 v[196:199], v150 offset:19456
	ds_read_b128 v[214:217], v150 offset:20480
	ds_read_b128 v[218:221], v150 offset:21504
	ds_read_b128 v[222:225], v150 offset:22528
	ds_read_b128 v[226:229], v150 offset:23552
	global_load_lds_dwordx4 v[146:147], off
	s_add_i32 m0, s70, 0x2000
	s_add_u32 s70, s42, 0x18000
	v_lshl_add_u64 v[204:205], s[42:43], 0, v[136:137]
	s_addc_u32 s71, s43, 0
	s_add_i32 s72, s72, s10
	global_load_lds_dwordx4 v[204:205], off
	v_lshl_add_u64 v[206:207], s[70:71], 0, v[98:99]
	s_mov_b32 m0, s72
	v_lshl_add_u64 v[208:209], s[54:55], 0, v[134:135]
	global_load_lds_dwordx4 v[206:207], off
	v_lshl_add_u64 v[206:207], s[70:71], 0, v[136:137]
	s_add_i32 m0, s72, 0x2000
	s_nop 0
	global_load_lds_dwordx4 v[206:207], off
	v_lshl_add_u64 v[206:207], s[54:55], 0, v[132:133]
	s_mov_b32 m0, s11
	s_nop 0
	global_load_lds_dwordx4 v[206:207], off
	s_mov_b32 m0, s12
	s_nop 0
	global_load_lds_dwordx4 v[208:209], off
	s_waitcnt vmcnt(8)
	s_waitcnt lgkmcnt(0)
	s_setprio 1
	s_barrier
	v_mfma_f32_16x16x32_bf16 v[62:65], v[152:155], v[184:187], v[62:65]
	v_mfma_f32_16x16x32_bf16 v[58:61], v[160:163], v[184:187], v[58:61]
	v_mfma_f32_16x16x32_bf16 v[46:49], v[152:155], v[192:195], v[46:49]
	v_mfma_f32_16x16x32_bf16 v[42:45], v[160:163], v[192:195], v[42:45]
	v_mfma_f32_16x16x32_bf16 v[30:33], v[152:155], v[214:217], v[30:33]
	v_mfma_f32_16x16x32_bf16 v[26:29], v[160:163], v[214:217], v[26:29]
	v_mfma_f32_16x16x32_bf16 v[14:17], v[152:155], v[222:225], v[14:17]
	v_mfma_f32_16x16x32_bf16 v[10:13], v[160:163], v[222:225], v[10:13]
	v_mfma_f32_16x16x32_bf16 v[62:65], v[156:159], v[188:191], v[62:65]
	v_mfma_f32_16x16x32_bf16 v[58:61], v[164:167], v[188:191], v[58:61]
	v_mfma_f32_16x16x32_bf16 v[46:49], v[156:159], v[196:199], v[46:49]
	v_mfma_f32_16x16x32_bf16 v[42:45], v[164:167], v[196:199], v[42:45]
	v_mfma_f32_16x16x32_bf16 v[30:33], v[156:159], v[218:221], v[30:33]
	v_mfma_f32_16x16x32_bf16 v[26:29], v[164:167], v[218:221], v[26:29]
	v_mfma_f32_16x16x32_bf16 v[14:17], v[156:159], v[226:229], v[14:17]
	v_mfma_f32_16x16x32_bf16 v[10:13], v[164:167], v[226:229], v[10:13]
	s_setprio 0
	s_setprio 1
	v_mfma_f32_16x16x32_bf16 v[54:57], v[168:171], v[184:187], v[54:57]
	v_mfma_f32_16x16x32_bf16 v[50:53], v[176:179], v[184:187], v[50:53]
	v_mfma_f32_16x16x32_bf16 v[38:41], v[168:171], v[192:195], v[38:41]
	v_mfma_f32_16x16x32_bf16 v[34:37], v[176:179], v[192:195], v[34:37]
	v_mfma_f32_16x16x32_bf16 v[22:25], v[168:171], v[214:217], v[22:25]
	v_mfma_f32_16x16x32_bf16 v[18:21], v[176:179], v[214:217], v[18:21]
	v_mfma_f32_16x16x32_bf16 v[6:9], v[168:171], v[222:225], v[6:9]
	v_mfma_f32_16x16x32_bf16 v[2:5], v[176:179], v[222:225], v[2:5]
	v_mfma_f32_16x16x32_bf16 v[54:57], v[172:175], v[188:191], v[54:57]
	v_mfma_f32_16x16x32_bf16 v[50:53], v[180:183], v[188:191], v[50:53]
	v_mfma_f32_16x16x32_bf16 v[38:41], v[172:175], v[196:199], v[38:41]
	v_mfma_f32_16x16x32_bf16 v[34:37], v[180:183], v[196:199], v[34:37]
	v_mfma_f32_16x16x32_bf16 v[22:25], v[172:175], v[218:221], v[22:25]
	v_mfma_f32_16x16x32_bf16 v[18:21], v[180:183], v[218:221], v[18:21]
	v_mfma_f32_16x16x32_bf16 v[6:9], v[172:175], v[226:229], v[6:9]
	v_mfma_f32_16x16x32_bf16 v[2:5], v[180:183], v[226:229], v[2:5]
	s_setprio 0
	s_barrier
	s_add_i32 s70, 0, 0x18000
	v_add_u32_e32 v151, s70, v149
	s_add_i32 s71, 0, 0x1c000
	ds_read_b128 v[152:155], v151
	ds_read_b128 v[156:159], v151 offset:1024
	ds_read_b128 v[160:163], v151 offset:2048
	ds_read_b128 v[164:167], v151 offset:3072
	v_add_u32_e32 v151, s71, v149
	ds_read_b128 v[168:171], v151
	ds_read_b128 v[172:175], v151 offset:1024
	ds_read_b128 v[176:179], v151 offset:2048
	ds_read_b128 v[180:183], v151 offset:3072
	s_add_u32 s54, s54, 0x80000
	s_addc_u32 s55, s55, 0
	s_mov_b32 m0, s13
	v_lshl_add_u64 v[210:211], s[54:55], 0, v[132:133]
	ds_read_b128 v[184:187], v150 offset:32768
	ds_read_b128 v[188:191], v150 offset:33792
	ds_read_b128 v[192:195], v150 offset:34816
	ds_read_b128 v[196:199], v150 offset:35840
	ds_read_b128 v[214:217], v150 offset:36864
	ds_read_b128 v[218:221], v150 offset:37888
	ds_read_b128 v[222:225], v150 offset:38912
	ds_read_b128 v[226:229], v150 offset:39936
	global_load_lds_dwordx4 v[210:211], off
	v_lshl_add_u64 v[210:211], s[54:55], 0, v[134:135]
	s_mov_b32 m0, s14
	s_nop 0
	global_load_lds_dwordx4 v[210:211], off
	s_waitcnt vmcnt(8)
	s_waitcnt lgkmcnt(0)
	s_setprio 1
	s_barrier
	v_mfma_f32_16x16x32_bf16 v[128:131], v[152:155], v[184:187], v[128:131]
	v_mfma_f32_16x16x32_bf16 v[124:127], v[160:163], v[184:187], v[124:127]
	v_mfma_f32_16x16x32_bf16 v[112:115], v[152:155], v[192:195], v[112:115]
	v_mfma_f32_16x16x32_bf16 v[108:111], v[160:163], v[192:195], v[108:111]
	v_mfma_f32_16x16x32_bf16 v[94:97], v[152:155], v[214:217], v[94:97]
	v_mfma_f32_16x16x32_bf16 v[90:93], v[160:163], v[214:217], v[90:93]
	v_mfma_f32_16x16x32_bf16 v[78:81], v[152:155], v[222:225], v[78:81]
	v_mfma_f32_16x16x32_bf16 v[74:77], v[160:163], v[222:225], v[74:77]
	v_mfma_f32_16x16x32_bf16 v[128:131], v[156:159], v[188:191], v[128:131]
	v_mfma_f32_16x16x32_bf16 v[124:127], v[164:167], v[188:191], v[124:127]
	v_mfma_f32_16x16x32_bf16 v[112:115], v[156:159], v[196:199], v[112:115]
	v_mfma_f32_16x16x32_bf16 v[108:111], v[164:167], v[196:199], v[108:111]
	v_mfma_f32_16x16x32_bf16 v[94:97], v[156:159], v[218:221], v[94:97]
	v_mfma_f32_16x16x32_bf16 v[90:93], v[164:167], v[218:221], v[90:93]
	v_mfma_f32_16x16x32_bf16 v[78:81], v[156:159], v[226:229], v[78:81]
	v_mfma_f32_16x16x32_bf16 v[74:77], v[164:167], v[226:229], v[74:77]
	s_setprio 0
	s_setprio 1
	v_mfma_f32_16x16x32_bf16 v[120:123], v[168:171], v[184:187], v[120:123]
	v_mfma_f32_16x16x32_bf16 v[116:119], v[176:179], v[184:187], v[116:119]
	v_mfma_f32_16x16x32_bf16 v[104:107], v[168:171], v[192:195], v[104:107]
	v_mfma_f32_16x16x32_bf16 v[100:103], v[176:179], v[192:195], v[100:103]
	v_mfma_f32_16x16x32_bf16 v[86:89], v[168:171], v[214:217], v[86:89]
	v_mfma_f32_16x16x32_bf16 v[82:85], v[176:179], v[214:217], v[82:85]
	v_mfma_f32_16x16x32_bf16 v[70:73], v[168:171], v[222:225], v[70:73]
	v_mfma_f32_16x16x32_bf16 v[66:69], v[176:179], v[222:225], v[66:69]
	v_mfma_f32_16x16x32_bf16 v[120:123], v[172:175], v[188:191], v[120:123]
	v_mfma_f32_16x16x32_bf16 v[116:119], v[180:183], v[188:191], v[116:119]
	v_mfma_f32_16x16x32_bf16 v[104:107], v[172:175], v[196:199], v[104:107]
	v_mfma_f32_16x16x32_bf16 v[100:103], v[180:183], v[196:199], v[100:103]
	v_mfma_f32_16x16x32_bf16 v[86:89], v[172:175], v[218:221], v[86:89]
	v_mfma_f32_16x16x32_bf16 v[82:85], v[180:183], v[218:221], v[82:85]
	v_mfma_f32_16x16x32_bf16 v[70:73], v[172:175], v[226:229], v[70:73]
	v_mfma_f32_16x16x32_bf16 v[66:69], v[180:183], v[226:229], v[66:69]
	s_setprio 0
	s_barrier
	s_add_i32 s54, s70, s10
	v_lshl_add_u64 v[146:147], v[146:147], 0, s[28:29]
	s_mov_b32 m0, s54
	ds_read_b128 v[184:187], v150 offset:49152
	ds_read_b128 v[188:191], v150 offset:50176
	ds_read_b128 v[192:195], v150 offset:51200
	ds_read_b128 v[196:199], v150 offset:52224
	ds_read_b128 v[214:217], v150 offset:53248
	ds_read_b128 v[218:221], v150 offset:54272
	ds_read_b128 v[222:225], v150 offset:55296
	ds_read_b128 v[226:229], v150 offset:56320
	global_load_lds_dwordx4 v[146:147], off
	s_add_i32 m0, s54, 0x2000
	s_add_u32 s42, s42, 0x18080
	v_lshl_add_u64 v[146:147], v[204:205], 0, s[28:29]
	s_addc_u32 s43, s43, 0
	s_add_i32 s54, s71, s10
	global_load_lds_dwordx4 v[146:147], off
	v_lshl_add_u64 v[146:147], s[42:43], 0, v[98:99]
	s_mov_b32 m0, s54
	s_nop 0
	global_load_lds_dwordx4 v[146:147], off
	v_lshl_add_u64 v[146:147], s[42:43], 0, v[136:137]
	s_add_i32 m0, s54, 0x2000
	s_nop 0
	global_load_lds_dwordx4 v[146:147], off
	v_lshl_add_u64 v[146:147], v[206:207], 0, s[28:29]
	s_mov_b32 m0, s17
	s_nop 0
	global_load_lds_dwordx4 v[146:147], off
	v_lshl_add_u64 v[146:147], v[208:209], 0, s[28:29]
	s_mov_b32 m0, s18
	s_nop 0
	global_load_lds_dwordx4 v[146:147], off
	s_waitcnt vmcnt(8)
	s_waitcnt lgkmcnt(0)
	s_setprio 1
	s_barrier
	v_mfma_f32_16x16x32_bf16 v[62:65], v[152:155], v[184:187], v[62:65]
	v_mfma_f32_16x16x32_bf16 v[58:61], v[160:163], v[184:187], v[58:61]
	v_mfma_f32_16x16x32_bf16 v[46:49], v[152:155], v[192:195], v[46:49]
	v_mfma_f32_16x16x32_bf16 v[42:45], v[160:163], v[192:195], v[42:45]
	v_mfma_f32_16x16x32_bf16 v[30:33], v[152:155], v[214:217], v[30:33]
	v_mfma_f32_16x16x32_bf16 v[26:29], v[160:163], v[214:217], v[26:29]
	v_mfma_f32_16x16x32_bf16 v[14:17], v[152:155], v[222:225], v[14:17]
	v_mfma_f32_16x16x32_bf16 v[10:13], v[160:163], v[222:225], v[10:13]
	v_mfma_f32_16x16x32_bf16 v[62:65], v[156:159], v[188:191], v[62:65]
	v_mfma_f32_16x16x32_bf16 v[58:61], v[164:167], v[188:191], v[58:61]
	v_mfma_f32_16x16x32_bf16 v[46:49], v[156:159], v[196:199], v[46:49]
	v_mfma_f32_16x16x32_bf16 v[42:45], v[164:167], v[196:199], v[42:45]
	v_mfma_f32_16x16x32_bf16 v[30:33], v[156:159], v[218:221], v[30:33]
	v_mfma_f32_16x16x32_bf16 v[26:29], v[164:167], v[218:221], v[26:29]
	v_mfma_f32_16x16x32_bf16 v[14:17], v[156:159], v[226:229], v[14:17]
	v_mfma_f32_16x16x32_bf16 v[10:13], v[164:167], v[226:229], v[10:13]
	s_setprio 0
	s_setprio 1
	v_mfma_f32_16x16x32_bf16 v[54:57], v[168:171], v[184:187], v[54:57]
	v_mfma_f32_16x16x32_bf16 v[50:53], v[176:179], v[184:187], v[50:53]
	v_mfma_f32_16x16x32_bf16 v[38:41], v[168:171], v[192:195], v[38:41]
	v_mfma_f32_16x16x32_bf16 v[34:37], v[176:179], v[192:195], v[34:37]
	v_mfma_f32_16x16x32_bf16 v[22:25], v[168:171], v[214:217], v[22:25]
	v_mfma_f32_16x16x32_bf16 v[18:21], v[176:179], v[214:217], v[18:21]
	v_mfma_f32_16x16x32_bf16 v[6:9], v[168:171], v[222:225], v[6:9]
	v_mfma_f32_16x16x32_bf16 v[2:5], v[176:179], v[222:225], v[2:5]
	v_mfma_f32_16x16x32_bf16 v[54:57], v[172:175], v[188:191], v[54:57]
	v_mfma_f32_16x16x32_bf16 v[50:53], v[180:183], v[188:191], v[50:53]
	v_mfma_f32_16x16x32_bf16 v[38:41], v[172:175], v[196:199], v[38:41]
	v_mfma_f32_16x16x32_bf16 v[34:37], v[180:183], v[196:199], v[34:37]
	v_mfma_f32_16x16x32_bf16 v[22:25], v[172:175], v[218:221], v[22:25]
	v_mfma_f32_16x16x32_bf16 v[18:21], v[180:183], v[218:221], v[18:21]
	v_mfma_f32_16x16x32_bf16 v[6:9], v[172:175], v[226:229], v[6:9]
	v_mfma_f32_16x16x32_bf16 v[2:5], v[180:183], v[226:229], v[2:5]
	s_setprio 0
	s_barrier
	s_add_u32 s40, s40, 0x100
	s_addc_u32 s41, s41, 0
	s_add_u32 s66, s66, 0x100
	s_addc_u32 s67, s67, 0
	s_cmp_ge_i32 s68, s62
	s_mov_b32 s42, s68
	s_cbranch_scc0 .LBB0_647
	s_and_b64 vcc, exec, s[44:45]
	s_cbranch_vccz .LBB0_650
	s_barrier

.LBB0_893:
	s_add_u32 s50, s48, 0xfffe0080
	s_addc_u32 s51, s49, -1
	s_add_i32 s57, 0, 0x10000
	s_cmp_eq_u32 s56, 4
	s_cselect_b32 s53, s19, s51
	s_cselect_b32 s52, s33, s50
	v_add_u32_e32 v98, s57, v144
	s_cselect_b32 s51, s37, s55
	s_cselect_b32 s50, s39, s54
	s_add_i32 s60, 0, 0x14000
	ds_read_b128 v[146:149], v98
	ds_read_b128 v[150:153], v98 offset:1024
	ds_read_b128 v[154:157], v98 offset:2048
	ds_read_b128 v[158:161], v98 offset:3072
	v_add_u32_e32 v98, s60, v144
	ds_read_b128 v[162:165], v98
	ds_read_b128 v[166:169], v98 offset:1024
	ds_read_b128 v[170:173], v98 offset:2048
	ds_read_b128 v[174:177], v98 offset:3072
	v_lshl_add_u64 v[198:199], s[48:49], 0, v[140:141]
	s_add_i32 m0, s4, 0xc000
	ds_read_b128 v[178:181], v145
	ds_read_b128 v[182:185], v145 offset:1024
	ds_read_b128 v[186:189], v145 offset:2048
	ds_read_b128 v[190:193], v145 offset:3072
	ds_read_b128 v[194:197], v145 offset:4096
	ds_read_b128 v[204:207], v145 offset:5120
	ds_read_b128 v[208:211], v145 offset:6144
	ds_read_b128 v[214:217], v145 offset:7168
	global_load_lds_dwordx4 v[198:199], off
	v_lshl_add_u64 v[198:199], s[48:49], 0, v[142:143]
	s_add_i32 m0, s4, 0xe000
	s_nop 0
	global_load_lds_dwordx4 v[198:199], off
	s_waitcnt vmcnt(8)
	s_waitcnt lgkmcnt(0)
	s_setprio 1
	s_barrier
	v_mfma_f32_16x16x32_bf16 v[128:131], v[146:149], v[178:181], v[128:131]
	v_mfma_f32_16x16x32_bf16 v[124:127], v[154:157], v[178:181], v[124:127]
	v_mfma_f32_16x16x32_bf16 v[112:115], v[146:149], v[186:189], v[112:115]
	v_mfma_f32_16x16x32_bf16 v[108:111], v[154:157], v[186:189], v[108:111]
	v_mfma_f32_16x16x32_bf16 v[94:97], v[146:149], v[194:197], v[94:97]
	v_mfma_f32_16x16x32_bf16 v[90:93], v[154:157], v[194:197], v[90:93]
	v_mfma_f32_16x16x32_bf16 v[78:81], v[146:149], v[208:211], v[78:81]
	v_mfma_f32_16x16x32_bf16 v[74:77], v[154:157], v[208:211], v[74:77]
	v_mfma_f32_16x16x32_bf16 v[128:131], v[150:153], v[182:185], v[128:131]
	v_mfma_f32_16x16x32_bf16 v[124:127], v[158:161], v[182:185], v[124:127]
	v_mfma_f32_16x16x32_bf16 v[112:115], v[150:153], v[190:193], v[112:115]
	v_mfma_f32_16x16x32_bf16 v[108:111], v[158:161], v[190:193], v[108:111]
	v_mfma_f32_16x16x32_bf16 v[94:97], v[150:153], v[204:207], v[94:97]
	v_mfma_f32_16x16x32_bf16 v[90:93], v[158:161], v[204:207], v[90:93]
	v_mfma_f32_16x16x32_bf16 v[78:81], v[150:153], v[214:217], v[78:81]
	v_mfma_f32_16x16x32_bf16 v[74:77], v[158:161], v[214:217], v[74:77]
	s_setprio 0
	s_setprio 1
	v_mfma_f32_16x16x32_bf16 v[120:123], v[162:165], v[178:181], v[120:123]
	v_mfma_f32_16x16x32_bf16 v[116:119], v[170:173], v[178:181], v[116:119]
	v_mfma_f32_16x16x32_bf16 v[104:107], v[162:165], v[186:189], v[104:107]
	v_mfma_f32_16x16x32_bf16 v[100:103], v[170:173], v[186:189], v[100:103]
	v_mfma_f32_16x16x32_bf16 v[86:89], v[162:165], v[194:197], v[86:89]
	v_mfma_f32_16x16x32_bf16 v[82:85], v[170:173], v[194:197], v[82:85]
	v_mfma_f32_16x16x32_bf16 v[70:73], v[162:165], v[208:211], v[70:73]
	v_mfma_f32_16x16x32_bf16 v[66:69], v[170:173], v[208:211], v[66:69]
	v_mfma_f32_16x16x32_bf16 v[120:123], v[166:169], v[182:185], v[120:123]
	v_mfma_f32_16x16x32_bf16 v[116:119], v[174:177], v[182:185], v[116:119]
	v_mfma_f32_16x16x32_bf16 v[104:107], v[166:169], v[190:193], v[104:107]
	v_mfma_f32_16x16x32_bf16 v[100:103], v[174:177], v[190:193], v[100:103]
	v_mfma_f32_16x16x32_bf16 v[86:89], v[166:169], v[204:207], v[86:89]
	v_mfma_f32_16x16x32_bf16 v[82:85], v[174:177], v[204:207], v[82:85]
	v_mfma_f32_16x16x32_bf16 v[70:73], v[166:169], v[214:217], v[70:73]
	v_mfma_f32_16x16x32_bf16 v[66:69], v[174:177], v[214:217], v[66:69]
	s_setprio 0
	s_barrier
	s_add_i32 s57, s57, s2
	v_lshl_add_u64 v[198:199], s[50:51], 0, v[136:137]
	s_mov_b32 m0, s57
	ds_read_b128 v[178:181], v145 offset:16384
	ds_read_b128 v[182:185], v145 offset:17408
	ds_read_b128 v[186:189], v145 offset:18432
	ds_read_b128 v[190:193], v145 offset:19456
	ds_read_b128 v[194:197], v145 offset:20480
	ds_read_b128 v[204:207], v145 offset:21504
	ds_read_b128 v[208:211], v145 offset:22528
	ds_read_b128 v[214:217], v145 offset:23552
	global_load_lds_dwordx4 v[198:199], off
	s_add_i32 m0, s57, 0x2000
	s_add_u32 s58, s50, 0x20000
	v_lshl_add_u64 v[218:219], s[50:51], 0, v[132:133]
	s_addc_u32 s59, s51, 0
	s_add_i32 s57, s60, s2
	global_load_lds_dwordx4 v[218:219], off
	v_lshl_add_u64 v[220:221], s[58:59], 0, v[136:137]
	s_mov_b32 m0, s57
	v_lshl_add_u64 v[222:223], s[52:53], 0, v[134:135]
	global_load_lds_dwordx4 v[220:221], off
	v_lshl_add_u64 v[220:221], s[58:59], 0, v[132:133]
	s_add_i32 m0, s57, 0x2000
	s_nop 0
	global_load_lds_dwordx4 v[220:221], off
	v_lshl_add_u64 v[220:221], s[52:53], 0, v[138:139]
	s_mov_b32 m0, s4
	s_nop 0
	global_load_lds_dwordx4 v[220:221], off
	s_mov_b32 m0, s7
	s_nop 0
	global_load_lds_dwordx4 v[222:223], off
	s_waitcnt vmcnt(8)
	s_waitcnt lgkmcnt(0)
	s_setprio 1
	s_barrier
	v_mfma_f32_16x16x32_bf16 v[62:65], v[146:149], v[178:181], v[62:65]
	v_mfma_f32_16x16x32_bf16 v[58:61], v[154:157], v[178:181], v[58:61]
	v_mfma_f32_16x16x32_bf16 v[46:49], v[146:149], v[186:189], v[46:49]
	v_mfma_f32_16x16x32_bf16 v[42:45], v[154:157], v[186:189], v[42:45]
	v_mfma_f32_16x16x32_bf16 v[30:33], v[146:149], v[194:197], v[30:33]
	v_mfma_f32_16x16x32_bf16 v[26:29], v[154:157], v[194:197], v[26:29]
	v_mfma_f32_16x16x32_bf16 v[14:17], v[146:149], v[208:211], v[14:17]
	v_mfma_f32_16x16x32_bf16 v[10:13], v[154:157], v[208:211], v[10:13]
	v_mfma_f32_16x16x32_bf16 v[62:65], v[150:153], v[182:185], v[62:65]
	v_mfma_f32_16x16x32_bf16 v[58:61], v[158:161], v[182:185], v[58:61]
	v_mfma_f32_16x16x32_bf16 v[46:49], v[150:153], v[190:193], v[46:49]
	v_mfma_f32_16x16x32_bf16 v[42:45], v[158:161], v[190:193], v[42:45]
	v_mfma_f32_16x16x32_bf16 v[30:33], v[150:153], v[204:207], v[30:33]
	v_mfma_f32_16x16x32_bf16 v[26:29], v[158:161], v[204:207], v[26:29]
	v_mfma_f32_16x16x32_bf16 v[14:17], v[150:153], v[214:217], v[14:17]
	v_mfma_f32_16x16x32_bf16 v[10:13], v[158:161], v[214:217], v[10:13]
	s_setprio 0
	s_setprio 1
	v_mfma_f32_16x16x32_bf16 v[54:57], v[162:165], v[178:181], v[54:57]
	v_mfma_f32_16x16x32_bf16 v[50:53], v[170:173], v[178:181], v[50:53]
	v_mfma_f32_16x16x32_bf16 v[38:41], v[162:165], v[186:189], v[38:41]
	v_mfma_f32_16x16x32_bf16 v[34:37], v[170:173], v[186:189], v[34:37]
	v_mfma_f32_16x16x32_bf16 v[22:25], v[162:165], v[194:197], v[22:25]
	v_mfma_f32_16x16x32_bf16 v[18:21], v[170:173], v[194:197], v[18:21]
	v_mfma_f32_16x16x32_bf16 v[6:9], v[162:165], v[208:211], v[6:9]
	v_mfma_f32_16x16x32_bf16 v[2:5], v[170:173], v[208:211], v[2:5]
	v_mfma_f32_16x16x32_bf16 v[54:57], v[166:169], v[182:185], v[54:57]
	v_mfma_f32_16x16x32_bf16 v[50:53], v[174:177], v[182:185], v[50:53]
	v_mfma_f32_16x16x32_bf16 v[38:41], v[166:169], v[190:193], v[38:41]
	v_mfma_f32_16x16x32_bf16 v[34:37], v[174:177], v[190:193], v[34:37]
	v_mfma_f32_16x16x32_bf16 v[22:25], v[166:169], v[204:207], v[22:25]
	v_mfma_f32_16x16x32_bf16 v[18:21], v[174:177], v[204:207], v[18:21]
	v_mfma_f32_16x16x32_bf16 v[6:9], v[166:169], v[214:217], v[6:9]
	v_mfma_f32_16x16x32_bf16 v[2:5], v[174:177], v[214:217], v[2:5]
	s_setprio 0
	s_barrier
	s_add_i32 s57, 0, 0x18000
	v_add_u32_e32 v98, s57, v144
	s_add_i32 s58, 0, 0x1c000
	ds_read_b128 v[146:149], v98
	ds_read_b128 v[150:153], v98 offset:1024
	ds_read_b128 v[154:157], v98 offset:2048
	ds_read_b128 v[158:161], v98 offset:3072
	v_add_u32_e32 v98, s58, v144
	ds_read_b128 v[162:165], v98
	ds_read_b128 v[166:169], v98 offset:1024
	ds_read_b128 v[170:173], v98 offset:2048
	ds_read_b128 v[174:177], v98 offset:3072
	s_add_u32 s52, s52, 0x20000
	s_addc_u32 s53, s53, 0
	s_mov_b32 m0, s8
	v_lshl_add_u64 v[224:225], s[52:53], 0, v[138:139]
	ds_read_b128 v[178:181], v145 offset:32768
	ds_read_b128 v[182:185], v145 offset:33792
	ds_read_b128 v[186:189], v145 offset:34816
	ds_read_b128 v[190:193], v145 offset:35840
	ds_read_b128 v[194:197], v145 offset:36864
	ds_read_b128 v[204:207], v145 offset:37888
	ds_read_b128 v[208:211], v145 offset:38912
	ds_read_b128 v[214:217], v145 offset:39936
	global_load_lds_dwordx4 v[224:225], off
	v_lshl_add_u64 v[224:225], s[52:53], 0, v[134:135]
	s_mov_b32 m0, s9
	s_nop 0
	global_load_lds_dwordx4 v[224:225], off
	s_waitcnt vmcnt(8)
	s_waitcnt lgkmcnt(0)
	s_setprio 1
	s_barrier
	v_mfma_f32_16x16x32_bf16 v[128:131], v[146:149], v[178:181], v[128:131]
	v_mfma_f32_16x16x32_bf16 v[124:127], v[154:157], v[178:181], v[124:127]
	v_mfma_f32_16x16x32_bf16 v[112:115], v[146:149], v[186:189], v[112:115]
	v_mfma_f32_16x16x32_bf16 v[108:111], v[154:157], v[186:189], v[108:111]
	v_mfma_f32_16x16x32_bf16 v[94:97], v[146:149], v[194:197], v[94:97]
	v_mfma_f32_16x16x32_bf16 v[90:93], v[154:157], v[194:197], v[90:93]
	v_mfma_f32_16x16x32_bf16 v[78:81], v[146:149], v[208:211], v[78:81]
	v_mfma_f32_16x16x32_bf16 v[74:77], v[154:157], v[208:211], v[74:77]
	v_mfma_f32_16x16x32_bf16 v[128:131], v[150:153], v[182:185], v[128:131]
	v_mfma_f32_16x16x32_bf16 v[124:127], v[158:161], v[182:185], v[124:127]
	v_mfma_f32_16x16x32_bf16 v[112:115], v[150:153], v[190:193], v[112:115]
	v_mfma_f32_16x16x32_bf16 v[108:111], v[158:161], v[190:193], v[108:111]
	v_mfma_f32_16x16x32_bf16 v[94:97], v[150:153], v[204:207], v[94:97]
	v_mfma_f32_16x16x32_bf16 v[90:93], v[158:161], v[204:207], v[90:93]
	v_mfma_f32_16x16x32_bf16 v[78:81], v[150:153], v[214:217], v[78:81]
	v_mfma_f32_16x16x32_bf16 v[74:77], v[158:161], v[214:217], v[74:77]
	s_setprio 0
	s_setprio 1
	v_mfma_f32_16x16x32_bf16 v[120:123], v[162:165], v[178:181], v[120:123]
	v_mfma_f32_16x16x32_bf16 v[116:119], v[170:173], v[178:181], v[116:119]
	v_mfma_f32_16x16x32_bf16 v[104:107], v[162:165], v[186:189], v[104:107]
	v_mfma_f32_16x16x32_bf16 v[100:103], v[170:173], v[186:189], v[100:103]
	v_mfma_f32_16x16x32_bf16 v[86:89], v[162:165], v[194:197], v[86:89]
	v_mfma_f32_16x16x32_bf16 v[82:85], v[170:173], v[194:197], v[82:85]
	v_mfma_f32_16x16x32_bf16 v[70:73], v[162:165], v[208:211], v[70:73]
	v_mfma_f32_16x16x32_bf16 v[66:69], v[170:173], v[208:211], v[66:69]
	v_mfma_f32_16x16x32_bf16 v[120:123], v[166:169], v[182:185], v[120:123]
	v_mfma_f32_16x16x32_bf16 v[116:119], v[174:177], v[182:185], v[116:119]
	v_mfma_f32_16x16x32_bf16 v[104:107], v[166:169], v[190:193], v[104:107]
	v_mfma_f32_16x16x32_bf16 v[100:103], v[174:177], v[190:193], v[100:103]
	v_mfma_f32_16x16x32_bf16 v[86:89], v[166:169], v[204:207], v[86:89]
	v_mfma_f32_16x16x32_bf16 v[82:85], v[174:177], v[204:207], v[82:85]
	v_mfma_f32_16x16x32_bf16 v[70:73], v[166:169], v[214:217], v[70:73]
	v_mfma_f32_16x16x32_bf16 v[66:69], v[174:177], v[214:217], v[66:69]
	s_setprio 0
	s_barrier
	s_add_i32 s52, s57, s2
	v_lshl_add_u64 v[198:199], v[198:199], 0, s[28:29]
	s_mov_b32 m0, s52
	ds_read_b128 v[178:181], v145 offset:49152
	ds_read_b128 v[182:185], v145 offset:50176
	ds_read_b128 v[186:189], v145 offset:51200
	ds_read_b128 v[190:193], v145 offset:52224
	ds_read_b128 v[194:197], v145 offset:53248
	ds_read_b128 v[204:207], v145 offset:54272
	ds_read_b128 v[208:211], v145 offset:55296
	ds_read_b128 v[214:217], v145 offset:56320
	global_load_lds_dwordx4 v[198:199], off
	s_add_i32 m0, s52, 0x2000
	s_add_u32 s50, s50, 0x20080
	v_lshl_add_u64 v[198:199], v[218:219], 0, s[28:29]
	s_addc_u32 s51, s51, 0
	s_add_i32 s52, s58, s2
	global_load_lds_dwordx4 v[198:199], off
	v_lshl_add_u64 v[198:199], s[50:51], 0, v[136:137]
	s_mov_b32 m0, s52
	s_nop 0
	global_load_lds_dwordx4 v[198:199], off
	v_lshl_add_u64 v[198:199], s[50:51], 0, v[132:133]
	s_add_i32 m0, s52, 0x2000
	s_nop 0
	global_load_lds_dwordx4 v[198:199], off
	v_lshl_add_u64 v[198:199], v[220:221], 0, s[28:29]
	s_mov_b32 m0, s12
	s_nop 0
	global_load_lds_dwordx4 v[198:199], off
	v_lshl_add_u64 v[198:199], v[222:223], 0, s[28:29]
	s_mov_b32 m0, s13
	s_nop 0
	global_load_lds_dwordx4 v[198:199], off
	s_waitcnt vmcnt(8)
	s_waitcnt lgkmcnt(0)
	s_setprio 1
	s_barrier
	v_mfma_f32_16x16x32_bf16 v[62:65], v[146:149], v[178:181], v[62:65]
	v_mfma_f32_16x16x32_bf16 v[58:61], v[154:157], v[178:181], v[58:61]
	v_mfma_f32_16x16x32_bf16 v[46:49], v[146:149], v[186:189], v[46:49]
	v_mfma_f32_16x16x32_bf16 v[42:45], v[154:157], v[186:189], v[42:45]
	v_mfma_f32_16x16x32_bf16 v[30:33], v[146:149], v[194:197], v[30:33]
	v_mfma_f32_16x16x32_bf16 v[26:29], v[154:157], v[194:197], v[26:29]
	v_mfma_f32_16x16x32_bf16 v[14:17], v[146:149], v[208:211], v[14:17]
	v_mfma_f32_16x16x32_bf16 v[10:13], v[154:157], v[208:211], v[10:13]
	v_mfma_f32_16x16x32_bf16 v[62:65], v[150:153], v[182:185], v[62:65]
	v_mfma_f32_16x16x32_bf16 v[58:61], v[158:161], v[182:185], v[58:61]
	v_mfma_f32_16x16x32_bf16 v[46:49], v[150:153], v[190:193], v[46:49]
	v_mfma_f32_16x16x32_bf16 v[42:45], v[158:161], v[190:193], v[42:45]
	v_mfma_f32_16x16x32_bf16 v[30:33], v[150:153], v[204:207], v[30:33]
	v_mfma_f32_16x16x32_bf16 v[26:29], v[158:161], v[204:207], v[26:29]
	v_mfma_f32_16x16x32_bf16 v[14:17], v[150:153], v[214:217], v[14:17]
	v_mfma_f32_16x16x32_bf16 v[10:13], v[158:161], v[214:217], v[10:13]
	s_setprio 0
	s_setprio 1
	v_mfma_f32_16x16x32_bf16 v[54:57], v[162:165], v[178:181], v[54:57]
	v_mfma_f32_16x16x32_bf16 v[50:53], v[170:173], v[178:181], v[50:53]
	v_mfma_f32_16x16x32_bf16 v[38:41], v[162:165], v[186:189], v[38:41]
	v_mfma_f32_16x16x32_bf16 v[34:37], v[170:173], v[186:189], v[34:37]
	v_mfma_f32_16x16x32_bf16 v[22:25], v[162:165], v[194:197], v[22:25]
	v_mfma_f32_16x16x32_bf16 v[18:21], v[170:173], v[194:197], v[18:21]
	v_mfma_f32_16x16x32_bf16 v[6:9], v[162:165], v[208:211], v[6:9]
	v_mfma_f32_16x16x32_bf16 v[2:5], v[170:173], v[208:211], v[2:5]
	v_mfma_f32_16x16x32_bf16 v[54:57], v[166:169], v[182:185], v[54:57]
	v_mfma_f32_16x16x32_bf16 v[50:53], v[174:177], v[182:185], v[50:53]
	v_mfma_f32_16x16x32_bf16 v[38:41], v[166:169], v[190:193], v[38:41]
	v_mfma_f32_16x16x32_bf16 v[34:37], v[174:177], v[190:193], v[34:37]
	v_mfma_f32_16x16x32_bf16 v[22:25], v[166:169], v[204:207], v[22:25]
	v_mfma_f32_16x16x32_bf16 v[18:21], v[174:177], v[204:207], v[18:21]
	v_mfma_f32_16x16x32_bf16 v[6:9], v[166:169], v[214:217], v[6:9]
	v_mfma_f32_16x16x32_bf16 v[2:5], v[174:177], v[214:217], v[2:5]
	s_setprio 0
	s_barrier
	s_add_i32 s56, s56, 2
	s_add_u32 s48, s48, 0x100
	s_addc_u32 s49, s49, 0
	s_add_u32 s54, s54, 0x100
	s_addc_u32 s55, s55, 0
	s_cmp_gt_u32 s56, 5
	s_cbranch_scc0 .LBB0_893
	s_and_b64 vcc, exec, s[22:23]
	s_cbranch_vccz .LBB0_896
	s_barrier

.LBB0_1072:
	s_add_u32 s60, s56, s58
	s_addc_u32 s61, s57, s59
	s_add_u32 s60, s60, 0x100
	s_addc_u32 s61, s61, 0
	s_add_u32 s71, s66, s58
	s_addc_u32 s72, s67, s59
	s_add_i32 s73, 0, 0x10000
	s_cmpk_eq_i32 s58, 0x700
	s_cselect_b32 s63, s45, s61
	s_cselect_b32 s62, s51, s60
	v_add_u32_e32 v98, s73, v214
	s_cselect_b32 s61, s49, s72
	s_cselect_b32 s60, s65, s71
	s_add_i32 s71, 0, 0x14000
	ds_read_b128 v[138:141], v98
	ds_read_b128 v[142:145], v98 offset:1024
	ds_read_b128 v[146:149], v98 offset:2048
	ds_read_b128 v[150:153], v98 offset:3072
	v_add_u32_e32 v98, s71, v214
	ds_read_b128 v[154:157], v98
	ds_read_b128 v[158:161], v98 offset:1024
	ds_read_b128 v[162:165], v98 offset:2048
	ds_read_b128 v[166:169], v98 offset:3072
	v_lshl_add_u64 v[100:101], v[134:135], 0, s[58:59]
	s_add_i32 m0, s9, 0xc000
	ds_read_b128 v[170:173], v218
	ds_read_b128 v[186:189], v218 offset:1024
	ds_read_b128 v[190:193], v218 offset:2048
	ds_read_b128 v[194:197], v218 offset:3072
	ds_read_b128 v[204:207], v218 offset:4096
	ds_read_b128 v[208:211], v218 offset:5120
	ds_read_b128 v[220:223], v218 offset:6144
	ds_read_b128 v[224:227], v218 offset:7168
	global_load_lds_dwordx4 v[100:101], off
	v_lshl_add_u64 v[100:101], v[136:137], 0, s[58:59]
	s_add_i32 m0, s9, 0xe000
	s_nop 0
	global_load_lds_dwordx4 v[100:101], off
	s_waitcnt vmcnt(8)
	s_waitcnt lgkmcnt(0)
	s_setprio 1
	s_barrier
	v_mfma_f32_16x16x32_bf16 v[130:133], v[138:141], v[170:173], v[130:133]
	v_mfma_f32_16x16x32_bf16 v[126:129], v[146:149], v[170:173], v[126:129]
	v_mfma_f32_16x16x32_bf16 v[122:125], v[138:141], v[190:193], v[122:125]
	v_mfma_f32_16x16x32_bf16 v[118:121], v[146:149], v[190:193], v[118:121]
	v_mfma_f32_16x16x32_bf16 v[114:117], v[138:141], v[204:207], v[114:117]
	v_mfma_f32_16x16x32_bf16 v[110:113], v[146:149], v[204:207], v[110:113]
	v_mfma_f32_16x16x32_bf16 v[106:109], v[138:141], v[220:223], v[106:109]
	v_mfma_f32_16x16x32_bf16 v[100:103], v[146:149], v[220:223], v[102:105]
	v_mfma_f32_16x16x32_bf16 v[130:133], v[142:145], v[186:189], v[130:133]
	v_mfma_f32_16x16x32_bf16 v[126:129], v[150:153], v[186:189], v[126:129]
	v_mfma_f32_16x16x32_bf16 v[122:125], v[142:145], v[194:197], v[122:125]
	v_mfma_f32_16x16x32_bf16 v[118:121], v[150:153], v[194:197], v[118:121]
	v_mfma_f32_16x16x32_bf16 v[114:117], v[142:145], v[208:211], v[114:117]
	v_mfma_f32_16x16x32_bf16 v[110:113], v[150:153], v[208:211], v[110:113]
	v_mfma_f32_16x16x32_bf16 v[106:109], v[142:145], v[224:227], v[106:109]
	v_mfma_f32_16x16x32_bf16 v[100:103], v[150:153], v[224:227], v[100:103]
	s_setprio 0
	s_setprio 1
	v_mfma_f32_16x16x32_bf16 v[62:65], v[154:157], v[170:173], v[62:65]
	v_mfma_f32_16x16x32_bf16 v[58:61], v[162:165], v[170:173], v[58:61]
	v_mfma_f32_16x16x32_bf16 v[54:57], v[154:157], v[190:193], v[54:57]
	v_mfma_f32_16x16x32_bf16 v[50:53], v[162:165], v[190:193], v[50:53]
	v_mfma_f32_16x16x32_bf16 v[46:49], v[154:157], v[204:207], v[46:49]
	v_mfma_f32_16x16x32_bf16 v[42:45], v[162:165], v[204:207], v[42:45]
	v_mfma_f32_16x16x32_bf16 v[38:41], v[154:157], v[220:223], v[38:41]
	v_mfma_f32_16x16x32_bf16 v[34:37], v[162:165], v[220:223], v[34:37]
	v_mfma_f32_16x16x32_bf16 v[62:65], v[158:161], v[186:189], v[62:65]
	v_mfma_f32_16x16x32_bf16 v[58:61], v[166:169], v[186:189], v[58:61]
	v_mfma_f32_16x16x32_bf16 v[54:57], v[158:161], v[194:197], v[54:57]
	v_mfma_f32_16x16x32_bf16 v[50:53], v[166:169], v[194:197], v[50:53]
	v_mfma_f32_16x16x32_bf16 v[46:49], v[158:161], v[208:211], v[46:49]
	v_mfma_f32_16x16x32_bf16 v[42:45], v[166:169], v[208:211], v[42:45]
	v_mfma_f32_16x16x32_bf16 v[38:41], v[158:161], v[224:227], v[38:41]
	v_mfma_f32_16x16x32_bf16 v[34:37], v[166:169], v[224:227], v[34:37]
	s_setprio 0
	s_barrier
	s_add_i32 s72, s73, s4
	v_lshl_add_u64 v[198:199], s[60:61], 0, v[176:177]
	s_mov_b32 m0, s72
	ds_read_b128 v[170:173], v218 offset:16384
	ds_read_b128 v[186:189], v218 offset:17408
	ds_read_b128 v[190:193], v218 offset:18432
	ds_read_b128 v[194:197], v218 offset:19456
	ds_read_b128 v[204:207], v218 offset:20480
	ds_read_b128 v[208:211], v218 offset:21504
	ds_read_b128 v[220:223], v218 offset:22528
	ds_read_b128 v[224:227], v218 offset:23552
	global_load_lds_dwordx4 v[198:199], off
	s_add_i32 m0, s72, 0x2000
	s_add_u32 s72, s60, 0x40000
	v_lshl_add_u64 v[228:229], s[60:61], 0, v[180:181]
	s_addc_u32 s73, s61, 0
	s_add_i32 s71, s71, s4
	global_load_lds_dwordx4 v[228:229], off
	v_lshl_add_u64 v[104:105], s[72:73], 0, v[176:177]
	s_mov_b32 m0, s71
	v_lshl_add_u64 v[230:231], s[62:63], 0, v[174:175]
	global_load_lds_dwordx4 v[104:105], off
	v_lshl_add_u64 v[104:105], s[72:73], 0, v[180:181]
	s_add_i32 m0, s71, 0x2000
	v_lshl_add_u64 v[232:233], s[62:63], 0, v[178:179]
	global_load_lds_dwordx4 v[104:105], off
	s_mov_b32 m0, s9
	s_nop 0
	global_load_lds_dwordx4 v[230:231], off
	s_mov_b32 m0, s10
	s_nop 0
	global_load_lds_dwordx4 v[232:233], off
	s_waitcnt vmcnt(8)
	s_waitcnt lgkmcnt(0)
	s_setprio 1
	s_barrier
	v_mfma_f32_16x16x32_bf16 v[94:97], v[138:141], v[170:173], v[94:97]
	v_mfma_f32_16x16x32_bf16 v[90:93], v[146:149], v[170:173], v[90:93]
	v_mfma_f32_16x16x32_bf16 v[86:89], v[138:141], v[190:193], v[86:89]
	v_mfma_f32_16x16x32_bf16 v[82:85], v[146:149], v[190:193], v[82:85]
	v_mfma_f32_16x16x32_bf16 v[78:81], v[138:141], v[204:207], v[78:81]
	v_mfma_f32_16x16x32_bf16 v[74:77], v[146:149], v[204:207], v[74:77]
	v_mfma_f32_16x16x32_bf16 v[70:73], v[138:141], v[220:223], v[70:73]
	v_mfma_f32_16x16x32_bf16 v[66:69], v[146:149], v[220:223], v[66:69]
	v_mfma_f32_16x16x32_bf16 v[94:97], v[142:145], v[186:189], v[94:97]
	v_mfma_f32_16x16x32_bf16 v[90:93], v[150:153], v[186:189], v[90:93]
	v_mfma_f32_16x16x32_bf16 v[86:89], v[142:145], v[194:197], v[86:89]
	v_mfma_f32_16x16x32_bf16 v[82:85], v[150:153], v[194:197], v[82:85]
	v_mfma_f32_16x16x32_bf16 v[78:81], v[142:145], v[208:211], v[78:81]
	v_mfma_f32_16x16x32_bf16 v[74:77], v[150:153], v[208:211], v[74:77]
	v_mfma_f32_16x16x32_bf16 v[70:73], v[142:145], v[224:227], v[70:73]
	v_mfma_f32_16x16x32_bf16 v[66:69], v[150:153], v[224:227], v[66:69]
	s_setprio 0
	s_setprio 1
	v_mfma_f32_16x16x32_bf16 v[30:33], v[154:157], v[170:173], v[30:33]
	v_mfma_f32_16x16x32_bf16 v[26:29], v[162:165], v[170:173], v[26:29]
	v_mfma_f32_16x16x32_bf16 v[22:25], v[154:157], v[190:193], v[22:25]
	v_mfma_f32_16x16x32_bf16 v[18:21], v[162:165], v[190:193], v[18:21]
	v_mfma_f32_16x16x32_bf16 v[14:17], v[154:157], v[204:207], v[14:17]
	v_mfma_f32_16x16x32_bf16 v[10:13], v[162:165], v[204:207], v[10:13]
	v_mfma_f32_16x16x32_bf16 v[6:9], v[154:157], v[220:223], v[6:9]
	v_mfma_f32_16x16x32_bf16 v[2:5], v[162:165], v[220:223], v[2:5]
	v_mfma_f32_16x16x32_bf16 v[30:33], v[158:161], v[186:189], v[30:33]
	v_mfma_f32_16x16x32_bf16 v[26:29], v[166:169], v[186:189], v[26:29]
	v_mfma_f32_16x16x32_bf16 v[22:25], v[158:161], v[194:197], v[22:25]
	v_mfma_f32_16x16x32_bf16 v[18:21], v[166:169], v[194:197], v[18:21]
	v_mfma_f32_16x16x32_bf16 v[14:17], v[158:161], v[208:211], v[14:17]
	v_mfma_f32_16x16x32_bf16 v[10:13], v[166:169], v[208:211], v[10:13]
	v_mfma_f32_16x16x32_bf16 v[6:9], v[158:161], v[224:227], v[6:9]
	v_mfma_f32_16x16x32_bf16 v[2:5], v[166:169], v[224:227], v[2:5]
	s_setprio 0
	s_barrier
	s_add_i32 s71, 0, 0x18000
	v_add_u32_e32 v98, s71, v214
	s_add_i32 s72, 0, 0x1c000
	ds_read_b128 v[138:141], v98
	ds_read_b128 v[142:145], v98 offset:1024
	ds_read_b128 v[146:149], v98 offset:2048
	ds_read_b128 v[150:153], v98 offset:3072
	v_add_u32_e32 v98, s72, v214
	ds_read_b128 v[154:157], v98
	ds_read_b128 v[158:161], v98 offset:1024
	ds_read_b128 v[162:165], v98 offset:2048
	ds_read_b128 v[166:169], v98 offset:3072
	s_add_u32 s62, s62, 0x40000
	s_addc_u32 s63, s63, 0
	s_mov_b32 m0, s11
	v_lshl_add_u64 v[104:105], s[62:63], 0, v[174:175]
	ds_read_b128 v[170:173], v218 offset:32768
	ds_read_b128 v[186:189], v218 offset:33792
	ds_read_b128 v[190:193], v218 offset:34816
	ds_read_b128 v[194:197], v218 offset:35840
	ds_read_b128 v[204:207], v218 offset:36864
	ds_read_b128 v[208:211], v218 offset:37888
	ds_read_b128 v[220:223], v218 offset:38912
	ds_read_b128 v[224:227], v218 offset:39936
	global_load_lds_dwordx4 v[104:105], off
	v_lshl_add_u64 v[104:105], s[62:63], 0, v[178:179]
	s_mov_b32 m0, s12
	s_nop 0
	global_load_lds_dwordx4 v[104:105], off
	s_waitcnt vmcnt(8)
	s_waitcnt lgkmcnt(0)
	s_setprio 1
	s_barrier
	v_mfma_f32_16x16x32_bf16 v[130:133], v[138:141], v[170:173], v[130:133]
	v_mfma_f32_16x16x32_bf16 v[126:129], v[146:149], v[170:173], v[126:129]
	v_mfma_f32_16x16x32_bf16 v[122:125], v[138:141], v[190:193], v[122:125]
	v_mfma_f32_16x16x32_bf16 v[118:121], v[146:149], v[190:193], v[118:121]
	v_mfma_f32_16x16x32_bf16 v[114:117], v[138:141], v[204:207], v[114:117]
	v_mfma_f32_16x16x32_bf16 v[110:113], v[146:149], v[204:207], v[110:113]
	v_mfma_f32_16x16x32_bf16 v[104:107], v[138:141], v[220:223], v[106:109]
	v_mfma_f32_16x16x32_bf16 v[100:103], v[146:149], v[220:223], v[100:103]
	v_mfma_f32_16x16x32_bf16 v[130:133], v[142:145], v[186:189], v[130:133]
	v_mfma_f32_16x16x32_bf16 v[126:129], v[150:153], v[186:189], v[126:129]
	v_mfma_f32_16x16x32_bf16 v[122:125], v[142:145], v[194:197], v[122:125]
	v_mfma_f32_16x16x32_bf16 v[118:121], v[150:153], v[194:197], v[118:121]
	v_mfma_f32_16x16x32_bf16 v[114:117], v[142:145], v[208:211], v[114:117]
	v_mfma_f32_16x16x32_bf16 v[110:113], v[150:153], v[208:211], v[110:113]
	v_mfma_f32_16x16x32_bf16 v[106:109], v[142:145], v[224:227], v[104:107]
	v_mfma_f32_16x16x32_bf16 v[102:105], v[150:153], v[224:227], v[100:103]
	s_setprio 0
	s_setprio 1
	v_mfma_f32_16x16x32_bf16 v[62:65], v[154:157], v[170:173], v[62:65]
	v_mfma_f32_16x16x32_bf16 v[58:61], v[162:165], v[170:173], v[58:61]
	v_mfma_f32_16x16x32_bf16 v[54:57], v[154:157], v[190:193], v[54:57]
	v_mfma_f32_16x16x32_bf16 v[50:53], v[162:165], v[190:193], v[50:53]
	v_mfma_f32_16x16x32_bf16 v[46:49], v[154:157], v[204:207], v[46:49]
	v_mfma_f32_16x16x32_bf16 v[42:45], v[162:165], v[204:207], v[42:45]
	v_mfma_f32_16x16x32_bf16 v[38:41], v[154:157], v[220:223], v[38:41]
	v_mfma_f32_16x16x32_bf16 v[34:37], v[162:165], v[220:223], v[34:37]
	v_mfma_f32_16x16x32_bf16 v[62:65], v[158:161], v[186:189], v[62:65]
	v_mfma_f32_16x16x32_bf16 v[58:61], v[166:169], v[186:189], v[58:61]
	v_mfma_f32_16x16x32_bf16 v[54:57], v[158:161], v[194:197], v[54:57]
	v_mfma_f32_16x16x32_bf16 v[50:53], v[166:169], v[194:197], v[50:53]
	v_mfma_f32_16x16x32_bf16 v[46:49], v[158:161], v[208:211], v[46:49]
	v_mfma_f32_16x16x32_bf16 v[42:45], v[166:169], v[208:211], v[42:45]
	v_mfma_f32_16x16x32_bf16 v[38:41], v[158:161], v[224:227], v[38:41]
	v_mfma_f32_16x16x32_bf16 v[34:37], v[166:169], v[224:227], v[34:37]
	s_setprio 0
	s_barrier
	s_add_i32 s62, s71, s4
	v_lshl_add_u64 v[100:101], v[198:199], 0, s[28:29]
	s_mov_b32 m0, s62
	ds_read_b128 v[170:173], v218 offset:49152
	ds_read_b128 v[186:189], v218 offset:50176
	ds_read_b128 v[190:193], v218 offset:51200
	ds_read_b128 v[194:197], v218 offset:52224
	ds_read_b128 v[204:207], v218 offset:53248
	ds_read_b128 v[208:211], v218 offset:54272
	ds_read_b128 v[220:223], v218 offset:55296
	ds_read_b128 v[224:227], v218 offset:56320
	global_load_lds_dwordx4 v[100:101], off
	s_add_i32 m0, s62, 0x2000
	s_add_u32 s60, s60, 0x40080
	v_lshl_add_u64 v[100:101], v[228:229], 0, s[28:29]
	s_addc_u32 s61, s61, 0
	s_add_i32 s62, s72, s4
	global_load_lds_dwordx4 v[100:101], off
	v_lshl_add_u64 v[100:101], s[60:61], 0, v[176:177]
	s_mov_b32 m0, s62
	s_nop 0
	global_load_lds_dwordx4 v[100:101], off
	v_lshl_add_u64 v[100:101], s[60:61], 0, v[180:181]
	s_add_i32 m0, s62, 0x2000
	s_nop 0
	global_load_lds_dwordx4 v[100:101], off
	v_lshl_add_u64 v[100:101], v[230:231], 0, s[28:29]
	s_mov_b32 m0, s15
	s_nop 0
	global_load_lds_dwordx4 v[100:101], off
	v_lshl_add_u64 v[100:101], v[232:233], 0, s[28:29]
	s_mov_b32 m0, s16
	s_nop 0
	global_load_lds_dwordx4 v[100:101], off
	s_waitcnt vmcnt(8)
	s_waitcnt lgkmcnt(0)
	s_setprio 1
	s_barrier
	v_mfma_f32_16x16x32_bf16 v[94:97], v[138:141], v[170:173], v[94:97]
	v_mfma_f32_16x16x32_bf16 v[90:93], v[146:149], v[170:173], v[90:93]
	v_mfma_f32_16x16x32_bf16 v[86:89], v[138:141], v[190:193], v[86:89]
	v_mfma_f32_16x16x32_bf16 v[82:85], v[146:149], v[190:193], v[82:85]
	v_mfma_f32_16x16x32_bf16 v[78:81], v[138:141], v[204:207], v[78:81]
	v_mfma_f32_16x16x32_bf16 v[74:77], v[146:149], v[204:207], v[74:77]
	v_mfma_f32_16x16x32_bf16 v[70:73], v[138:141], v[220:223], v[70:73]
	v_mfma_f32_16x16x32_bf16 v[66:69], v[146:149], v[220:223], v[66:69]
	v_mfma_f32_16x16x32_bf16 v[94:97], v[142:145], v[186:189], v[94:97]
	v_mfma_f32_16x16x32_bf16 v[90:93], v[150:153], v[186:189], v[90:93]
	v_mfma_f32_16x16x32_bf16 v[86:89], v[142:145], v[194:197], v[86:89]
	v_mfma_f32_16x16x32_bf16 v[82:85], v[150:153], v[194:197], v[82:85]
	v_mfma_f32_16x16x32_bf16 v[78:81], v[142:145], v[208:211], v[78:81]
	v_mfma_f32_16x16x32_bf16 v[74:77], v[150:153], v[208:211], v[74:77]
	v_mfma_f32_16x16x32_bf16 v[70:73], v[142:145], v[224:227], v[70:73]
	v_mfma_f32_16x16x32_bf16 v[66:69], v[150:153], v[224:227], v[66:69]
	s_setprio 0
	s_setprio 1
	v_mfma_f32_16x16x32_bf16 v[30:33], v[154:157], v[170:173], v[30:33]
	v_mfma_f32_16x16x32_bf16 v[26:29], v[162:165], v[170:173], v[26:29]
	v_mfma_f32_16x16x32_bf16 v[22:25], v[154:157], v[190:193], v[22:25]
	v_mfma_f32_16x16x32_bf16 v[18:21], v[162:165], v[190:193], v[18:21]
	v_mfma_f32_16x16x32_bf16 v[14:17], v[154:157], v[204:207], v[14:17]
	v_mfma_f32_16x16x32_bf16 v[10:13], v[162:165], v[204:207], v[10:13]
	v_mfma_f32_16x16x32_bf16 v[6:9], v[154:157], v[220:223], v[6:9]
	v_mfma_f32_16x16x32_bf16 v[2:5], v[162:165], v[220:223], v[2:5]
	v_mfma_f32_16x16x32_bf16 v[30:33], v[158:161], v[186:189], v[30:33]
	v_mfma_f32_16x16x32_bf16 v[26:29], v[166:169], v[186:189], v[26:29]
	v_mfma_f32_16x16x32_bf16 v[22:25], v[158:161], v[194:197], v[22:25]
	v_mfma_f32_16x16x32_bf16 v[18:21], v[166:169], v[194:197], v[18:21]
	v_mfma_f32_16x16x32_bf16 v[14:17], v[158:161], v[208:211], v[14:17]
	v_mfma_f32_16x16x32_bf16 v[10:13], v[166:169], v[208:211], v[10:13]
	v_mfma_f32_16x16x32_bf16 v[6:9], v[158:161], v[224:227], v[6:9]
	v_mfma_f32_16x16x32_bf16 v[2:5], v[166:169], v[224:227], v[2:5]
	s_setprio 0
	s_barrier
	s_add_u32 s58, s58, 0x100
	s_addc_u32 s59, s59, 0
	s_cmp_gt_u32 s70, 13
	s_cbranch_scc1 .LBB0_1075

.LBB0_1110:
	s_add_i32 s75, s75, 2
	s_add_u32 s60, s38, s58
	s_addc_u32 s61, s39, s59
	s_add_u32 s60, s60, 0x100
	s_addc_u32 s61, s61, 0
	s_add_u32 s76, s72, s58
	s_addc_u32 s77, s73, s59
	s_add_i32 s78, 0, 0x10000
	s_cmp_eq_u32 s74, s58
	s_cselect_b32 s63, s49, s61
	s_cselect_b32 s62, s70, s60
	v_add_u32_e32 v98, s78, v177
	s_cselect_b32 s61, s45, s77
	s_cselect_b32 s60, s71, s76
	s_add_i32 s79, 0, 0x14000
	ds_read_b128 v[138:141], v98
	ds_read_b128 v[142:145], v98 offset:1024
	ds_read_b128 v[146:149], v98 offset:2048
	ds_read_b128 v[150:153], v98 offset:3072
	v_add_u32_e32 v98, s79, v177
	ds_read_b128 v[154:157], v98
	ds_read_b128 v[170:173], v98 offset:1024
	ds_read_b128 v[182:185], v98 offset:2048
	ds_read_b128 v[186:189], v98 offset:3072
	v_lshl_add_u64 v[100:101], v[134:135], 0, s[58:59]
	s_add_i32 m0, s10, 0xc000
	ds_read_b128 v[190:193], v181
	ds_read_b128 v[194:197], v181 offset:1024
	ds_read_b128 v[204:207], v181 offset:2048
	ds_read_b128 v[208:211], v181 offset:3072
	ds_read_b128 v[214:217], v181 offset:4096
	ds_read_b128 v[218:221], v181 offset:5120
	ds_read_b128 v[222:225], v181 offset:6144
	ds_read_b128 v[226:229], v181 offset:7168
	global_load_lds_dwordx4 v[100:101], off
	v_lshl_add_u64 v[100:101], v[136:137], 0, s[58:59]
	s_add_i32 m0, s10, 0xe000
	s_nop 0
	global_load_lds_dwordx4 v[100:101], off
	s_waitcnt vmcnt(8)
	s_waitcnt lgkmcnt(0)
	s_setprio 1
	s_barrier
	v_mfma_f32_16x16x32_bf16 v[130:133], v[138:141], v[190:193], v[130:133]
	v_mfma_f32_16x16x32_bf16 v[126:129], v[146:149], v[190:193], v[126:129]
	v_mfma_f32_16x16x32_bf16 v[114:117], v[138:141], v[204:207], v[114:117]
	v_mfma_f32_16x16x32_bf16 v[110:113], v[146:149], v[204:207], v[110:113]
	v_mfma_f32_16x16x32_bf16 v[94:97], v[138:141], v[214:217], v[94:97]
	v_mfma_f32_16x16x32_bf16 v[90:93], v[146:149], v[214:217], v[90:93]
	v_mfma_f32_16x16x32_bf16 v[78:81], v[138:141], v[222:225], v[78:81]
	v_mfma_f32_16x16x32_bf16 v[74:77], v[146:149], v[222:225], v[74:77]
	v_mfma_f32_16x16x32_bf16 v[130:133], v[142:145], v[194:197], v[130:133]
	v_mfma_f32_16x16x32_bf16 v[126:129], v[150:153], v[194:197], v[126:129]
	v_mfma_f32_16x16x32_bf16 v[114:117], v[142:145], v[208:211], v[114:117]
	v_mfma_f32_16x16x32_bf16 v[110:113], v[150:153], v[208:211], v[110:113]
	v_mfma_f32_16x16x32_bf16 v[94:97], v[142:145], v[218:221], v[94:97]
	v_mfma_f32_16x16x32_bf16 v[90:93], v[150:153], v[218:221], v[90:93]
	v_mfma_f32_16x16x32_bf16 v[78:81], v[142:145], v[226:229], v[78:81]
	v_mfma_f32_16x16x32_bf16 v[74:77], v[150:153], v[226:229], v[74:77]
	s_setprio 0
	s_setprio 1
	v_mfma_f32_16x16x32_bf16 v[122:125], v[154:157], v[190:193], v[122:125]
	v_mfma_f32_16x16x32_bf16 v[118:121], v[182:185], v[190:193], v[118:121]
	v_mfma_f32_16x16x32_bf16 v[106:109], v[154:157], v[204:207], v[106:109]
	v_mfma_f32_16x16x32_bf16 v[100:103], v[182:185], v[204:207], v[102:105]
	v_mfma_f32_16x16x32_bf16 v[86:89], v[154:157], v[214:217], v[86:89]
	v_mfma_f32_16x16x32_bf16 v[82:85], v[182:185], v[214:217], v[82:85]
	v_mfma_f32_16x16x32_bf16 v[70:73], v[154:157], v[222:225], v[70:73]
	v_mfma_f32_16x16x32_bf16 v[66:69], v[182:185], v[222:225], v[66:69]
	v_mfma_f32_16x16x32_bf16 v[122:125], v[170:173], v[194:197], v[122:125]
	v_mfma_f32_16x16x32_bf16 v[118:121], v[186:189], v[194:197], v[118:121]
	v_mfma_f32_16x16x32_bf16 v[106:109], v[170:173], v[208:211], v[106:109]
	v_mfma_f32_16x16x32_bf16 v[100:103], v[186:189], v[208:211], v[100:103]
	v_mfma_f32_16x16x32_bf16 v[86:89], v[170:173], v[218:221], v[86:89]
	v_mfma_f32_16x16x32_bf16 v[82:85], v[186:189], v[218:221], v[82:85]
	v_mfma_f32_16x16x32_bf16 v[70:73], v[170:173], v[226:229], v[70:73]
	v_mfma_f32_16x16x32_bf16 v[66:69], v[186:189], v[226:229], v[66:69]
	s_setprio 0
	s_barrier
	s_add_i32 s76, s78, s9
	v_lshl_add_u64 v[174:175], s[60:61], 0, v[162:163]
	s_mov_b32 m0, s76
	ds_read_b128 v[190:193], v181 offset:16384
	ds_read_b128 v[194:197], v181 offset:17408
	ds_read_b128 v[204:207], v181 offset:18432
	ds_read_b128 v[208:211], v181 offset:19456
	ds_read_b128 v[214:217], v181 offset:20480
	ds_read_b128 v[218:221], v181 offset:21504
	ds_read_b128 v[222:225], v181 offset:22528
	ds_read_b128 v[226:229], v181 offset:23552
	global_load_lds_dwordx4 v[174:175], off
	s_add_i32 m0, s76, 0x2000
	s_add_u32 s76, s60, 0x40000
	v_lshl_add_u64 v[198:199], s[60:61], 0, v[158:159]
	s_addc_u32 s77, s61, 0
	s_add_i32 s78, s79, s9
	global_load_lds_dwordx4 v[198:199], off
	v_lshl_add_u64 v[104:105], s[76:77], 0, v[162:163]
	s_mov_b32 m0, s78
	v_lshl_add_u64 v[230:231], s[62:63], 0, v[164:165]
	global_load_lds_dwordx4 v[104:105], off
	v_lshl_add_u64 v[104:105], s[76:77], 0, v[158:159]
	s_add_i32 m0, s78, 0x2000
	v_lshl_add_u64 v[232:233], s[62:63], 0, v[160:161]
	global_load_lds_dwordx4 v[104:105], off
	s_mov_b32 m0, s10
	s_nop 0
	global_load_lds_dwordx4 v[230:231], off
	s_mov_b32 m0, s11
	s_nop 0
	global_load_lds_dwordx4 v[232:233], off
	s_waitcnt vmcnt(8)
	s_waitcnt lgkmcnt(0)
	s_setprio 1
	s_barrier
	v_mfma_f32_16x16x32_bf16 v[62:65], v[138:141], v[190:193], v[62:65]
	v_mfma_f32_16x16x32_bf16 v[58:61], v[146:149], v[190:193], v[58:61]
	v_mfma_f32_16x16x32_bf16 v[46:49], v[138:141], v[204:207], v[46:49]
	v_mfma_f32_16x16x32_bf16 v[42:45], v[146:149], v[204:207], v[42:45]
	v_mfma_f32_16x16x32_bf16 v[30:33], v[138:141], v[214:217], v[30:33]
	v_mfma_f32_16x16x32_bf16 v[26:29], v[146:149], v[214:217], v[26:29]
	v_mfma_f32_16x16x32_bf16 v[14:17], v[138:141], v[222:225], v[14:17]
	v_mfma_f32_16x16x32_bf16 v[10:13], v[146:149], v[222:225], v[10:13]
	v_mfma_f32_16x16x32_bf16 v[62:65], v[142:145], v[194:197], v[62:65]
	v_mfma_f32_16x16x32_bf16 v[58:61], v[150:153], v[194:197], v[58:61]
	v_mfma_f32_16x16x32_bf16 v[46:49], v[142:145], v[208:211], v[46:49]
	v_mfma_f32_16x16x32_bf16 v[42:45], v[150:153], v[208:211], v[42:45]
	v_mfma_f32_16x16x32_bf16 v[30:33], v[142:145], v[218:221], v[30:33]
	v_mfma_f32_16x16x32_bf16 v[26:29], v[150:153], v[218:221], v[26:29]
	v_mfma_f32_16x16x32_bf16 v[14:17], v[142:145], v[226:229], v[14:17]
	v_mfma_f32_16x16x32_bf16 v[10:13], v[150:153], v[226:229], v[10:13]
	s_setprio 0
	s_setprio 1
	v_mfma_f32_16x16x32_bf16 v[54:57], v[154:157], v[190:193], v[54:57]
	v_mfma_f32_16x16x32_bf16 v[50:53], v[182:185], v[190:193], v[50:53]
	v_mfma_f32_16x16x32_bf16 v[38:41], v[154:157], v[204:207], v[38:41]
	v_mfma_f32_16x16x32_bf16 v[34:37], v[182:185], v[204:207], v[34:37]
	v_mfma_f32_16x16x32_bf16 v[22:25], v[154:157], v[214:217], v[22:25]
	v_mfma_f32_16x16x32_bf16 v[18:21], v[182:185], v[214:217], v[18:21]
	v_mfma_f32_16x16x32_bf16 v[6:9], v[154:157], v[222:225], v[6:9]
	v_mfma_f32_16x16x32_bf16 v[2:5], v[182:185], v[222:225], v[2:5]
	v_mfma_f32_16x16x32_bf16 v[54:57], v[170:173], v[194:197], v[54:57]
	v_mfma_f32_16x16x32_bf16 v[50:53], v[186:189], v[194:197], v[50:53]
	v_mfma_f32_16x16x32_bf16 v[38:41], v[170:173], v[208:211], v[38:41]
	v_mfma_f32_16x16x32_bf16 v[34:37], v[186:189], v[208:211], v[34:37]
	v_mfma_f32_16x16x32_bf16 v[22:25], v[170:173], v[218:221], v[22:25]
	v_mfma_f32_16x16x32_bf16 v[18:21], v[186:189], v[218:221], v[18:21]
	v_mfma_f32_16x16x32_bf16 v[6:9], v[170:173], v[226:229], v[6:9]
	v_mfma_f32_16x16x32_bf16 v[2:5], v[186:189], v[226:229], v[2:5]
	s_setprio 0
	s_barrier
	s_add_i32 s76, 0, 0x18000
	v_add_u32_e32 v98, s76, v177
	s_add_i32 s77, 0, 0x1c000
	ds_read_b128 v[138:141], v98
	ds_read_b128 v[142:145], v98 offset:1024
	ds_read_b128 v[146:149], v98 offset:2048
	ds_read_b128 v[150:153], v98 offset:3072
	v_add_u32_e32 v98, s77, v177
	ds_read_b128 v[154:157], v98
	ds_read_b128 v[170:173], v98 offset:1024
	ds_read_b128 v[182:185], v98 offset:2048
	ds_read_b128 v[186:189], v98 offset:3072
	s_add_u32 s62, s62, 0x40000
	s_addc_u32 s63, s63, 0
	s_mov_b32 m0, s12
	v_lshl_add_u64 v[104:105], s[62:63], 0, v[164:165]
	ds_read_b128 v[190:193], v181 offset:32768
	ds_read_b128 v[194:197], v181 offset:33792
	ds_read_b128 v[204:207], v181 offset:34816
	ds_read_b128 v[208:211], v181 offset:35840
	ds_read_b128 v[214:217], v181 offset:36864
	ds_read_b128 v[218:221], v181 offset:37888
	ds_read_b128 v[222:225], v181 offset:38912
	ds_read_b128 v[226:229], v181 offset:39936
	global_load_lds_dwordx4 v[104:105], off
	v_lshl_add_u64 v[104:105], s[62:63], 0, v[160:161]
	s_mov_b32 m0, s13
	s_nop 0
	global_load_lds_dwordx4 v[104:105], off
	s_waitcnt vmcnt(8)
	s_waitcnt lgkmcnt(0)
	s_setprio 1
	s_barrier
	v_mfma_f32_16x16x32_bf16 v[130:133], v[138:141], v[190:193], v[130:133]
	v_mfma_f32_16x16x32_bf16 v[126:129], v[146:149], v[190:193], v[126:129]
	v_mfma_f32_16x16x32_bf16 v[114:117], v[138:141], v[204:207], v[114:117]
	v_mfma_f32_16x16x32_bf16 v[110:113], v[146:149], v[204:207], v[110:113]
	v_mfma_f32_16x16x32_bf16 v[94:97], v[138:141], v[214:217], v[94:97]
	v_mfma_f32_16x16x32_bf16 v[90:93], v[146:149], v[214:217], v[90:93]
	v_mfma_f32_16x16x32_bf16 v[78:81], v[138:141], v[222:225], v[78:81]
	v_mfma_f32_16x16x32_bf16 v[74:77], v[146:149], v[222:225], v[74:77]
	v_mfma_f32_16x16x32_bf16 v[130:133], v[142:145], v[194:197], v[130:133]
	v_mfma_f32_16x16x32_bf16 v[126:129], v[150:153], v[194:197], v[126:129]
	v_mfma_f32_16x16x32_bf16 v[114:117], v[142:145], v[208:211], v[114:117]
	v_mfma_f32_16x16x32_bf16 v[110:113], v[150:153], v[208:211], v[110:113]
	v_mfma_f32_16x16x32_bf16 v[94:97], v[142:145], v[218:221], v[94:97]
	v_mfma_f32_16x16x32_bf16 v[90:93], v[150:153], v[218:221], v[90:93]
	v_mfma_f32_16x16x32_bf16 v[78:81], v[142:145], v[226:229], v[78:81]
	v_mfma_f32_16x16x32_bf16 v[74:77], v[150:153], v[226:229], v[74:77]
	s_setprio 0
	s_setprio 1
	v_mfma_f32_16x16x32_bf16 v[122:125], v[154:157], v[190:193], v[122:125]
	v_mfma_f32_16x16x32_bf16 v[118:121], v[182:185], v[190:193], v[118:121]
	v_mfma_f32_16x16x32_bf16 v[104:107], v[154:157], v[204:207], v[106:109]
	v_mfma_f32_16x16x32_bf16 v[100:103], v[182:185], v[204:207], v[100:103]
	v_mfma_f32_16x16x32_bf16 v[86:89], v[154:157], v[214:217], v[86:89]
	v_mfma_f32_16x16x32_bf16 v[82:85], v[182:185], v[214:217], v[82:85]
	v_mfma_f32_16x16x32_bf16 v[70:73], v[154:157], v[222:225], v[70:73]
	v_mfma_f32_16x16x32_bf16 v[66:69], v[182:185], v[222:225], v[66:69]
	v_mfma_f32_16x16x32_bf16 v[122:125], v[170:173], v[194:197], v[122:125]
	v_mfma_f32_16x16x32_bf16 v[118:121], v[186:189], v[194:197], v[118:121]
	v_mfma_f32_16x16x32_bf16 v[106:109], v[170:173], v[208:211], v[104:107]
	v_mfma_f32_16x16x32_bf16 v[102:105], v[186:189], v[208:211], v[100:103]
	v_mfma_f32_16x16x32_bf16 v[86:89], v[170:173], v[218:221], v[86:89]
	v_mfma_f32_16x16x32_bf16 v[82:85], v[186:189], v[218:221], v[82:85]
	v_mfma_f32_16x16x32_bf16 v[70:73], v[170:173], v[226:229], v[70:73]
	v_mfma_f32_16x16x32_bf16 v[66:69], v[186:189], v[226:229], v[66:69]
	s_setprio 0
	s_barrier
	s_add_i32 s62, s76, s9
	v_lshl_add_u64 v[100:101], v[174:175], 0, s[28:29]
	s_mov_b32 m0, s62
	ds_read_b128 v[190:193], v181 offset:49152
	ds_read_b128 v[194:197], v181 offset:50176
	ds_read_b128 v[204:207], v181 offset:51200
	ds_read_b128 v[208:211], v181 offset:52224
	ds_read_b128 v[214:217], v181 offset:53248
	ds_read_b128 v[218:221], v181 offset:54272
	ds_read_b128 v[222:225], v181 offset:55296
	ds_read_b128 v[226:229], v181 offset:56320
	global_load_lds_dwordx4 v[100:101], off
	s_add_i32 m0, s62, 0x2000
	s_add_u32 s60, s60, 0x40080
	v_lshl_add_u64 v[100:101], v[198:199], 0, s[28:29]
	s_addc_u32 s61, s61, 0
	s_add_i32 s62, s77, s9
	global_load_lds_dwordx4 v[100:101], off
	v_lshl_add_u64 v[100:101], s[60:61], 0, v[162:163]
	s_mov_b32 m0, s62
	s_nop 0
	global_load_lds_dwordx4 v[100:101], off
	v_lshl_add_u64 v[100:101], s[60:61], 0, v[158:159]
	s_add_i32 m0, s62, 0x2000
	s_nop 0
	global_load_lds_dwordx4 v[100:101], off
	v_lshl_add_u64 v[100:101], v[230:231], 0, s[28:29]
	s_mov_b32 m0, s16
	s_nop 0
	global_load_lds_dwordx4 v[100:101], off
	v_lshl_add_u64 v[100:101], v[232:233], 0, s[28:29]
	s_mov_b32 m0, s17
	s_nop 0
	global_load_lds_dwordx4 v[100:101], off
	s_waitcnt vmcnt(8)
	s_waitcnt lgkmcnt(0)
	s_setprio 1
	s_barrier
	v_mfma_f32_16x16x32_bf16 v[62:65], v[138:141], v[190:193], v[62:65]
	v_mfma_f32_16x16x32_bf16 v[58:61], v[146:149], v[190:193], v[58:61]
	v_mfma_f32_16x16x32_bf16 v[46:49], v[138:141], v[204:207], v[46:49]
	v_mfma_f32_16x16x32_bf16 v[42:45], v[146:149], v[204:207], v[42:45]
	v_mfma_f32_16x16x32_bf16 v[30:33], v[138:141], v[214:217], v[30:33]
	v_mfma_f32_16x16x32_bf16 v[26:29], v[146:149], v[214:217], v[26:29]
	v_mfma_f32_16x16x32_bf16 v[14:17], v[138:141], v[222:225], v[14:17]
	v_mfma_f32_16x16x32_bf16 v[10:13], v[146:149], v[222:225], v[10:13]
	v_mfma_f32_16x16x32_bf16 v[62:65], v[142:145], v[194:197], v[62:65]
	v_mfma_f32_16x16x32_bf16 v[58:61], v[150:153], v[194:197], v[58:61]
	v_mfma_f32_16x16x32_bf16 v[46:49], v[142:145], v[208:211], v[46:49]
	v_mfma_f32_16x16x32_bf16 v[42:45], v[150:153], v[208:211], v[42:45]
	v_mfma_f32_16x16x32_bf16 v[30:33], v[142:145], v[218:221], v[30:33]
	v_mfma_f32_16x16x32_bf16 v[26:29], v[150:153], v[218:221], v[26:29]
	v_mfma_f32_16x16x32_bf16 v[14:17], v[142:145], v[226:229], v[14:17]
	v_mfma_f32_16x16x32_bf16 v[10:13], v[150:153], v[226:229], v[10:13]
	s_setprio 0
	s_setprio 1
	v_mfma_f32_16x16x32_bf16 v[54:57], v[154:157], v[190:193], v[54:57]
	v_mfma_f32_16x16x32_bf16 v[50:53], v[182:185], v[190:193], v[50:53]
	v_mfma_f32_16x16x32_bf16 v[38:41], v[154:157], v[204:207], v[38:41]
	v_mfma_f32_16x16x32_bf16 v[34:37], v[182:185], v[204:207], v[34:37]
	v_mfma_f32_16x16x32_bf16 v[22:25], v[154:157], v[214:217], v[22:25]
	v_mfma_f32_16x16x32_bf16 v[18:21], v[182:185], v[214:217], v[18:21]
	v_mfma_f32_16x16x32_bf16 v[6:9], v[154:157], v[222:225], v[6:9]
	v_mfma_f32_16x16x32_bf16 v[2:5], v[182:185], v[222:225], v[2:5]
	v_mfma_f32_16x16x32_bf16 v[54:57], v[170:173], v[194:197], v[54:57]
	v_mfma_f32_16x16x32_bf16 v[50:53], v[186:189], v[194:197], v[50:53]
	v_mfma_f32_16x16x32_bf16 v[38:41], v[170:173], v[208:211], v[38:41]
	v_mfma_f32_16x16x32_bf16 v[34:37], v[186:189], v[208:211], v[34:37]
	v_mfma_f32_16x16x32_bf16 v[22:25], v[170:173], v[218:221], v[22:25]
	v_mfma_f32_16x16x32_bf16 v[18:21], v[186:189], v[218:221], v[18:21]
	v_mfma_f32_16x16x32_bf16 v[6:9], v[170:173], v[226:229], v[6:9]
	v_mfma_f32_16x16x32_bf16 v[2:5], v[186:189], v[226:229], v[2:5]
	s_setprio 0
	s_barrier
	s_add_u32 s58, s58, 0x100
	s_addc_u32 s59, s59, 0
	s_cmp_ge_u32 s75, s57
	s_cbranch_scc1 .LBB0_1113

.LBB0_1328:
	s_add_u32 s44, s42, 0xfffc0080
	s_addc_u32 s45, s43, -1
	s_add_i32 s53, 0, 0x10000
	s_cmp_eq_u32 s52, 12
	s_cselect_b32 s47, s1, s45
	s_cselect_b32 s46, s41, s44
	s_cselect_b32 s45, s48, s51
	s_cselect_b32 s44, s49, s50
	s_add_i32 s56, 0, 0x14000
	v_add_u32_e32 v94, s53, v186
	v_add_u32_e32 v174, s56, v186
	ds_read_b128 v[82:85], v94
	ds_read_b128 v[86:89], v94 offset:1024
	ds_read_b128 v[90:93], v94 offset:2048
	ds_read_b128 v[94:97], v94 offset:3072
	ds_read_b128 v[162:165], v174
	ds_read_b128 v[166:169], v174 offset:1024
	ds_read_b128 v[170:173], v174 offset:2048
	ds_read_b128 v[174:177], v174 offset:3072
	s_add_u32 s100, s42, 0xfffc0000
	s_addc_u32 s101, s43, -1
	v_lshl_add_u64 v[198:199], s[100:101], 0, v[148:149]
	s_mov_b32 m0, s33
	s_nop 0
	global_load_lds_dwordx4 v[198:199], off
	v_lshl_add_u64 v[198:199], s[100:101], 0, v[150:151]
	s_mov_b32 m0, s14
	s_nop 0
	global_load_lds_dwordx4 v[198:199], off
	v_lshl_add_u64 v[198:199], s[42:43], 0, v[158:159]
	s_add_i32 m0, s2, 0xc000
	ds_read_b128 v[178:181], v187
	ds_read_b128 v[182:185], v187 offset:1024
	ds_read_b128 v[190:193], v187 offset:2048
	ds_read_b128 v[194:197], v187 offset:3072
	ds_read_b128 v[204:207], v187 offset:4096
	ds_read_b128 v[208:211], v187 offset:5120
	ds_read_b128 v[214:217], v187 offset:6144
	ds_read_b128 v[218:221], v187 offset:7168
	global_load_lds_dwordx4 v[198:199], off
	v_lshl_add_u64 v[198:199], s[42:43], 0, v[160:161]
	s_add_i32 m0, s2, 0xe000
	s_nop 0
	global_load_lds_dwordx4 v[198:199], off
	s_waitcnt vmcnt(8)
	s_waitcnt lgkmcnt(0)
	s_setprio 1
	s_barrier
	v_mfma_f32_16x16x32_bf16 v[144:147], v[82:85], v[178:181], v[144:147]
	v_mfma_f32_16x16x32_bf16 v[140:143], v[90:93], v[178:181], v[140:143]
	v_mfma_f32_16x16x32_bf16 v[128:131], v[82:85], v[190:193], v[128:131]
	v_mfma_f32_16x16x32_bf16 v[124:127], v[90:93], v[190:193], v[124:127]
	v_mfma_f32_16x16x32_bf16 v[112:115], v[82:85], v[204:207], v[112:115]
	v_mfma_f32_16x16x32_bf16 v[108:111], v[90:93], v[204:207], v[108:111]
	v_mfma_f32_16x16x32_bf16 v[78:81], v[82:85], v[214:217], v[78:81]
	v_mfma_f32_16x16x32_bf16 v[74:77], v[90:93], v[214:217], v[74:77]
	v_mfma_f32_16x16x32_bf16 v[144:147], v[86:89], v[182:185], v[144:147]
	v_mfma_f32_16x16x32_bf16 v[140:143], v[94:97], v[182:185], v[140:143]
	v_mfma_f32_16x16x32_bf16 v[128:131], v[86:89], v[194:197], v[128:131]
	v_mfma_f32_16x16x32_bf16 v[124:127], v[94:97], v[194:197], v[124:127]
	v_mfma_f32_16x16x32_bf16 v[112:115], v[86:89], v[208:211], v[112:115]
	v_mfma_f32_16x16x32_bf16 v[108:111], v[94:97], v[208:211], v[108:111]
	v_mfma_f32_16x16x32_bf16 v[78:81], v[86:89], v[218:221], v[78:81]
	v_mfma_f32_16x16x32_bf16 v[74:77], v[94:97], v[218:221], v[74:77]
	s_setprio 0
	s_setprio 1
	v_mfma_f32_16x16x32_bf16 v[136:139], v[162:165], v[178:181], v[136:139]
	v_mfma_f32_16x16x32_bf16 v[132:135], v[170:173], v[178:181], v[132:135]
	v_mfma_f32_16x16x32_bf16 v[120:123], v[162:165], v[190:193], v[120:123]
	v_mfma_f32_16x16x32_bf16 v[116:119], v[170:173], v[190:193], v[116:119]
	v_mfma_f32_16x16x32_bf16 v[104:107], v[162:165], v[204:207], v[104:107]
	v_mfma_f32_16x16x32_bf16 v[100:103], v[170:173], v[204:207], v[100:103]
	v_mfma_f32_16x16x32_bf16 v[70:73], v[162:165], v[214:217], v[70:73]
	v_mfma_f32_16x16x32_bf16 v[66:69], v[170:173], v[214:217], v[66:69]
	v_mfma_f32_16x16x32_bf16 v[136:139], v[166:169], v[182:185], v[136:139]
	v_mfma_f32_16x16x32_bf16 v[132:135], v[174:177], v[182:185], v[132:135]
	v_mfma_f32_16x16x32_bf16 v[120:123], v[166:169], v[194:197], v[120:123]
	v_mfma_f32_16x16x32_bf16 v[116:119], v[174:177], v[194:197], v[116:119]
	v_mfma_f32_16x16x32_bf16 v[104:107], v[166:169], v[208:211], v[104:107]
	v_mfma_f32_16x16x32_bf16 v[100:103], v[174:177], v[208:211], v[100:103]
	v_mfma_f32_16x16x32_bf16 v[70:73], v[166:169], v[218:221], v[70:73]
	v_mfma_f32_16x16x32_bf16 v[66:69], v[174:177], v[218:221], v[66:69]
	s_setprio 0
	s_barrier
	s_add_i32 s53, s53, s9
	v_lshl_add_u64 v[198:199], s[44:45], 0, v[98:99]
	s_mov_b32 m0, s53
	ds_read_b128 v[178:181], v187 offset:16384
	ds_read_b128 v[182:185], v187 offset:17408
	ds_read_b128 v[190:193], v187 offset:18432
	ds_read_b128 v[194:197], v187 offset:19456
	ds_read_b128 v[204:207], v187 offset:20480
	ds_read_b128 v[208:211], v187 offset:21504
	ds_read_b128 v[214:217], v187 offset:22528
	ds_read_b128 v[218:221], v187 offset:23552
	global_load_lds_dwordx4 v[198:199], off
	s_add_i32 m0, s53, 0x2000
	s_add_u32 s54, s44, 0x40000
	v_lshl_add_u64 v[222:223], s[44:45], 0, v[152:153]
	s_addc_u32 s55, s45, 0
	s_add_i32 s53, s56, s9
	global_load_lds_dwordx4 v[222:223], off
	v_lshl_add_u64 v[224:225], s[54:55], 0, v[98:99]
	s_mov_b32 m0, s53
	s_nop 0
	global_load_lds_dwordx4 v[224:225], off
	v_lshl_add_u64 v[224:225], s[54:55], 0, v[152:153]
	s_add_i32 m0, s53, 0x2000
	s_nop 0
	global_load_lds_dwordx4 v[224:225], off
	s_waitcnt vmcnt(6)
	s_waitcnt lgkmcnt(0)
	s_setprio 1
	s_barrier
	v_mfma_f32_16x16x32_bf16 v[62:65], v[82:85], v[178:181], v[62:65]
	v_mfma_f32_16x16x32_bf16 v[58:61], v[90:93], v[178:181], v[58:61]
	v_mfma_f32_16x16x32_bf16 v[46:49], v[82:85], v[190:193], v[46:49]
	v_mfma_f32_16x16x32_bf16 v[42:45], v[90:93], v[190:193], v[42:45]
	v_mfma_f32_16x16x32_bf16 v[30:33], v[82:85], v[204:207], v[30:33]
	v_mfma_f32_16x16x32_bf16 v[26:29], v[90:93], v[204:207], v[26:29]
	v_mfma_f32_16x16x32_bf16 v[14:17], v[82:85], v[214:217], v[14:17]
	v_mfma_f32_16x16x32_bf16 v[10:13], v[90:93], v[214:217], v[10:13]
	v_mfma_f32_16x16x32_bf16 v[62:65], v[86:89], v[182:185], v[62:65]
	v_mfma_f32_16x16x32_bf16 v[58:61], v[94:97], v[182:185], v[58:61]
	v_mfma_f32_16x16x32_bf16 v[46:49], v[86:89], v[194:197], v[46:49]
	v_mfma_f32_16x16x32_bf16 v[42:45], v[94:97], v[194:197], v[42:45]
	v_mfma_f32_16x16x32_bf16 v[30:33], v[86:89], v[208:211], v[30:33]
	v_mfma_f32_16x16x32_bf16 v[26:29], v[94:97], v[208:211], v[26:29]
	v_mfma_f32_16x16x32_bf16 v[14:17], v[86:89], v[218:221], v[14:17]
	v_mfma_f32_16x16x32_bf16 v[10:13], v[94:97], v[218:221], v[10:13]
	s_setprio 0
	s_setprio 1
	v_mfma_f32_16x16x32_bf16 v[54:57], v[162:165], v[178:181], v[54:57]
	v_mfma_f32_16x16x32_bf16 v[50:53], v[170:173], v[178:181], v[50:53]
	v_mfma_f32_16x16x32_bf16 v[38:41], v[162:165], v[190:193], v[38:41]
	v_mfma_f32_16x16x32_bf16 v[34:37], v[170:173], v[190:193], v[34:37]
	v_mfma_f32_16x16x32_bf16 v[22:25], v[162:165], v[204:207], v[22:25]
	v_mfma_f32_16x16x32_bf16 v[18:21], v[170:173], v[204:207], v[18:21]
	v_mfma_f32_16x16x32_bf16 v[6:9], v[162:165], v[214:217], v[6:9]
	v_mfma_f32_16x16x32_bf16 v[2:5], v[170:173], v[214:217], v[2:5]
	v_mfma_f32_16x16x32_bf16 v[54:57], v[166:169], v[182:185], v[54:57]
	v_mfma_f32_16x16x32_bf16 v[50:53], v[174:177], v[182:185], v[50:53]
	v_mfma_f32_16x16x32_bf16 v[38:41], v[166:169], v[194:197], v[38:41]
	v_mfma_f32_16x16x32_bf16 v[34:37], v[174:177], v[194:197], v[34:37]
	v_mfma_f32_16x16x32_bf16 v[22:25], v[166:169], v[208:211], v[22:25]
	v_mfma_f32_16x16x32_bf16 v[18:21], v[174:177], v[208:211], v[18:21]
	v_mfma_f32_16x16x32_bf16 v[6:9], v[166:169], v[218:221], v[6:9]
	v_mfma_f32_16x16x32_bf16 v[2:5], v[174:177], v[218:221], v[2:5]
	s_setprio 0
	s_barrier
	s_add_i32 s53, 0, 0x18000
	s_add_i32 s54, 0, 0x1c000
	v_add_u32_e32 v94, s53, v186
	v_add_u32_e32 v174, s54, v186
	ds_read_b128 v[82:85], v94
	ds_read_b128 v[86:89], v94 offset:1024
	ds_read_b128 v[90:93], v94 offset:2048
	ds_read_b128 v[94:97], v94 offset:3072
	ds_read_b128 v[162:165], v174
	ds_read_b128 v[166:169], v174 offset:1024
	ds_read_b128 v[170:173], v174 offset:2048
	ds_read_b128 v[174:177], v174 offset:3072
	v_lshl_add_u64 v[224:225], s[46:47], 0, v[148:149]
	s_mov_b32 m0, s2
	v_lshl_add_u64 v[226:227], s[46:47], 0, v[150:151]
	global_load_lds_dwordx4 v[224:225], off
	s_mov_b32 m0, s4
	s_nop 0
	global_load_lds_dwordx4 v[226:227], off
	s_add_u32 s46, s46, 0x40000
	s_addc_u32 s47, s47, 0
	s_mov_b32 m0, s12
	v_lshl_add_u64 v[228:229], s[46:47], 0, v[148:149]
	ds_read_b128 v[178:181], v187 offset:32768
	ds_read_b128 v[182:185], v187 offset:33792
	ds_read_b128 v[190:193], v187 offset:34816
	ds_read_b128 v[194:197], v187 offset:35840
	ds_read_b128 v[204:207], v187 offset:36864
	ds_read_b128 v[208:211], v187 offset:37888
	ds_read_b128 v[214:217], v187 offset:38912
	ds_read_b128 v[218:221], v187 offset:39936
	global_load_lds_dwordx4 v[228:229], off
	v_lshl_add_u64 v[228:229], s[46:47], 0, v[150:151]
	s_mov_b32 m0, s13
	s_nop 0
	global_load_lds_dwordx4 v[228:229], off
	s_waitcnt vmcnt(8)
	s_waitcnt lgkmcnt(0)
	s_setprio 1
	s_barrier
	v_mfma_f32_16x16x32_bf16 v[144:147], v[82:85], v[178:181], v[144:147]
	v_mfma_f32_16x16x32_bf16 v[140:143], v[90:93], v[178:181], v[140:143]
	v_mfma_f32_16x16x32_bf16 v[128:131], v[82:85], v[190:193], v[128:131]
	v_mfma_f32_16x16x32_bf16 v[124:127], v[90:93], v[190:193], v[124:127]
	v_mfma_f32_16x16x32_bf16 v[112:115], v[82:85], v[204:207], v[112:115]
	v_mfma_f32_16x16x32_bf16 v[108:111], v[90:93], v[204:207], v[108:111]
	v_mfma_f32_16x16x32_bf16 v[78:81], v[82:85], v[214:217], v[78:81]
	v_mfma_f32_16x16x32_bf16 v[74:77], v[90:93], v[214:217], v[74:77]
	v_mfma_f32_16x16x32_bf16 v[144:147], v[86:89], v[182:185], v[144:147]
	v_mfma_f32_16x16x32_bf16 v[140:143], v[94:97], v[182:185], v[140:143]
	v_mfma_f32_16x16x32_bf16 v[128:131], v[86:89], v[194:197], v[128:131]
	v_mfma_f32_16x16x32_bf16 v[124:127], v[94:97], v[194:197], v[124:127]
	v_mfma_f32_16x16x32_bf16 v[112:115], v[86:89], v[208:211], v[112:115]
	v_mfma_f32_16x16x32_bf16 v[108:111], v[94:97], v[208:211], v[108:111]
	v_mfma_f32_16x16x32_bf16 v[78:81], v[86:89], v[218:221], v[78:81]
	v_mfma_f32_16x16x32_bf16 v[74:77], v[94:97], v[218:221], v[74:77]
	s_setprio 0
	s_setprio 1
	v_mfma_f32_16x16x32_bf16 v[136:139], v[162:165], v[178:181], v[136:139]
	v_mfma_f32_16x16x32_bf16 v[132:135], v[170:173], v[178:181], v[132:135]
	v_mfma_f32_16x16x32_bf16 v[120:123], v[162:165], v[190:193], v[120:123]
	v_mfma_f32_16x16x32_bf16 v[116:119], v[170:173], v[190:193], v[116:119]
	v_mfma_f32_16x16x32_bf16 v[104:107], v[162:165], v[204:207], v[104:107]
	v_mfma_f32_16x16x32_bf16 v[100:103], v[170:173], v[204:207], v[100:103]
	v_mfma_f32_16x16x32_bf16 v[70:73], v[162:165], v[214:217], v[70:73]
	v_mfma_f32_16x16x32_bf16 v[66:69], v[170:173], v[214:217], v[66:69]
	v_mfma_f32_16x16x32_bf16 v[136:139], v[166:169], v[182:185], v[136:139]
	v_mfma_f32_16x16x32_bf16 v[132:135], v[174:177], v[182:185], v[132:135]
	v_mfma_f32_16x16x32_bf16 v[120:123], v[166:169], v[194:197], v[120:123]
	v_mfma_f32_16x16x32_bf16 v[116:119], v[174:177], v[194:197], v[116:119]
	v_mfma_f32_16x16x32_bf16 v[104:107], v[166:169], v[208:211], v[104:107]
	v_mfma_f32_16x16x32_bf16 v[100:103], v[174:177], v[208:211], v[100:103]
	v_mfma_f32_16x16x32_bf16 v[70:73], v[166:169], v[218:221], v[70:73]
	v_mfma_f32_16x16x32_bf16 v[66:69], v[174:177], v[218:221], v[66:69]
	s_setprio 0
	s_barrier
	s_add_i32 s46, s53, s9
	v_lshl_add_u64 v[198:199], v[198:199], 0, s[28:29]
	s_mov_b32 m0, s46
	ds_read_b128 v[178:181], v187 offset:49152
	ds_read_b128 v[182:185], v187 offset:50176
	ds_read_b128 v[190:193], v187 offset:51200
	ds_read_b128 v[194:197], v187 offset:52224
	ds_read_b128 v[204:207], v187 offset:53248
	ds_read_b128 v[208:211], v187 offset:54272
	ds_read_b128 v[214:217], v187 offset:55296
	ds_read_b128 v[218:221], v187 offset:56320
	global_load_lds_dwordx4 v[198:199], off
	s_add_i32 m0, s46, 0x2000
	s_add_u32 s44, s44, 0x40080
	v_lshl_add_u64 v[198:199], v[222:223], 0, s[28:29]
	s_addc_u32 s45, s45, 0
	s_add_i32 s46, s54, s9
	global_load_lds_dwordx4 v[198:199], off
	v_lshl_add_u64 v[198:199], s[44:45], 0, v[98:99]
	s_mov_b32 m0, s46
	s_nop 0
	global_load_lds_dwordx4 v[198:199], off
	v_lshl_add_u64 v[198:199], s[44:45], 0, v[152:153]
	s_add_i32 m0, s46, 0x2000
	s_nop 0
	global_load_lds_dwordx4 v[198:199], off
	s_waitcnt vmcnt(6)
	s_waitcnt lgkmcnt(0)
	s_setprio 1
	s_barrier
	v_mfma_f32_16x16x32_bf16 v[62:65], v[82:85], v[178:181], v[62:65]
	v_mfma_f32_16x16x32_bf16 v[58:61], v[90:93], v[178:181], v[58:61]
	v_mfma_f32_16x16x32_bf16 v[46:49], v[82:85], v[190:193], v[46:49]
	v_mfma_f32_16x16x32_bf16 v[42:45], v[90:93], v[190:193], v[42:45]
	v_mfma_f32_16x16x32_bf16 v[30:33], v[82:85], v[204:207], v[30:33]
	v_mfma_f32_16x16x32_bf16 v[26:29], v[90:93], v[204:207], v[26:29]
	v_mfma_f32_16x16x32_bf16 v[14:17], v[82:85], v[214:217], v[14:17]
	v_mfma_f32_16x16x32_bf16 v[10:13], v[90:93], v[214:217], v[10:13]
	v_mfma_f32_16x16x32_bf16 v[62:65], v[86:89], v[182:185], v[62:65]
	v_mfma_f32_16x16x32_bf16 v[58:61], v[94:97], v[182:185], v[58:61]
	v_mfma_f32_16x16x32_bf16 v[46:49], v[86:89], v[194:197], v[46:49]
	v_mfma_f32_16x16x32_bf16 v[42:45], v[94:97], v[194:197], v[42:45]
	v_mfma_f32_16x16x32_bf16 v[30:33], v[86:89], v[208:211], v[30:33]
	v_mfma_f32_16x16x32_bf16 v[26:29], v[94:97], v[208:211], v[26:29]
	v_mfma_f32_16x16x32_bf16 v[14:17], v[86:89], v[218:221], v[14:17]
	v_mfma_f32_16x16x32_bf16 v[10:13], v[94:97], v[218:221], v[10:13]
	s_setprio 0
	s_setprio 1
	v_mfma_f32_16x16x32_bf16 v[54:57], v[162:165], v[178:181], v[54:57]
	v_mfma_f32_16x16x32_bf16 v[50:53], v[170:173], v[178:181], v[50:53]
	v_mfma_f32_16x16x32_bf16 v[38:41], v[162:165], v[190:193], v[38:41]
	v_mfma_f32_16x16x32_bf16 v[34:37], v[170:173], v[190:193], v[34:37]
	v_mfma_f32_16x16x32_bf16 v[22:25], v[162:165], v[204:207], v[22:25]
	v_mfma_f32_16x16x32_bf16 v[18:21], v[170:173], v[204:207], v[18:21]
	v_mfma_f32_16x16x32_bf16 v[6:9], v[162:165], v[214:217], v[6:9]
	v_mfma_f32_16x16x32_bf16 v[2:5], v[170:173], v[214:217], v[2:5]
	v_mfma_f32_16x16x32_bf16 v[54:57], v[166:169], v[182:185], v[54:57]
	v_mfma_f32_16x16x32_bf16 v[50:53], v[174:177], v[182:185], v[50:53]
	v_mfma_f32_16x16x32_bf16 v[38:41], v[166:169], v[194:197], v[38:41]
	v_mfma_f32_16x16x32_bf16 v[34:37], v[174:177], v[194:197], v[34:37]
	v_mfma_f32_16x16x32_bf16 v[22:25], v[166:169], v[208:211], v[22:25]
	v_mfma_f32_16x16x32_bf16 v[18:21], v[174:177], v[208:211], v[18:21]
	v_mfma_f32_16x16x32_bf16 v[6:9], v[166:169], v[218:221], v[6:9]
	v_mfma_f32_16x16x32_bf16 v[2:5], v[174:177], v[218:221], v[2:5]
	s_setprio 0
	s_barrier
	s_add_i32 s52, s52, 2
	s_add_u32 s42, s42, 0x100
	s_addc_u32 s43, s43, 0
	s_add_u32 s50, s50, 0x100
	s_addc_u32 s51, s51, 0
	s_cmp_gt_u32 s52, 13
	s_cbranch_scc0 .LBB0_1328
	s_and_b64 vcc, exec, s[76:77]
	s_cbranch_vccz .LBB0_1331
	s_barrier

.LBB0_1529:
	s_add_u32 s50, s48, 0x100
	s_addc_u32 s51, s49, 0
	s_add_i32 s58, 0, 0x10000
	s_cmp_eq_u32 s57, 40
	s_cselect_b32 s55, s1, s51
	s_cselect_b32 s54, s0, s50
	s_cselect_b32 s53, s47, s56
	s_cselect_b32 s52, s46, s33
	s_add_i32 s59, 0, 0x14000
	v_add_u32_e32 v144, s58, v186
	v_add_u32_e32 v160, s59, v186
	ds_read_b128 v[132:135], v144
	ds_read_b128 v[136:139], v144 offset:1024
	ds_read_b128 v[140:143], v144 offset:2048
	ds_read_b128 v[144:147], v144 offset:3072
	ds_read_b128 v[148:151], v160
	ds_read_b128 v[152:155], v160 offset:1024
	ds_read_b128 v[156:159], v160 offset:2048
	ds_read_b128 v[160:163], v160 offset:3072
	v_lshl_add_u64 v[214:215], s[48:49], 0, v[174:175]
	s_add_i32 m0, s4, 0xc000
	ds_read_b128 v[164:167], v187
	ds_read_b128 v[178:181], v187 offset:1024
	ds_read_b128 v[182:185], v187 offset:2048
	ds_read_b128 v[188:191], v187 offset:3072
	ds_read_b128 v[192:195], v187 offset:4096
	ds_read_b128 v[196:199], v187 offset:5120
	ds_read_b128 v[204:207], v187 offset:6144
	ds_read_b128 v[208:211], v187 offset:7168
	global_load_lds_dwordx4 v[214:215], off
	v_lshl_add_u64 v[214:215], s[48:49], 0, v[176:177]
	s_add_i32 m0, s4, 0xe000
	s_nop 0
	global_load_lds_dwordx4 v[214:215], off
	s_waitcnt vmcnt(8)
	s_waitcnt lgkmcnt(0)
	s_setprio 1
	s_barrier
	v_mfma_f32_16x16x32_bf16 v[128:131], v[132:135], v[164:167], v[128:131]
	v_mfma_f32_16x16x32_bf16 v[124:127], v[140:143], v[164:167], v[124:127]
	v_mfma_f32_16x16x32_bf16 v[120:123], v[132:135], v[182:185], v[120:123]
	v_mfma_f32_16x16x32_bf16 v[116:119], v[140:143], v[182:185], v[116:119]
	v_mfma_f32_16x16x32_bf16 v[112:115], v[132:135], v[192:195], v[112:115]
	v_mfma_f32_16x16x32_bf16 v[108:111], v[140:143], v[192:195], v[108:111]
	v_mfma_f32_16x16x32_bf16 v[104:107], v[132:135], v[204:207], v[104:107]
	v_mfma_f32_16x16x32_bf16 v[100:103], v[140:143], v[204:207], v[100:103]
	v_mfma_f32_16x16x32_bf16 v[128:131], v[136:139], v[178:181], v[128:131]
	v_mfma_f32_16x16x32_bf16 v[124:127], v[144:147], v[178:181], v[124:127]
	v_mfma_f32_16x16x32_bf16 v[120:123], v[136:139], v[188:191], v[120:123]
	v_mfma_f32_16x16x32_bf16 v[116:119], v[144:147], v[188:191], v[116:119]
	v_mfma_f32_16x16x32_bf16 v[112:115], v[136:139], v[196:199], v[112:115]
	v_mfma_f32_16x16x32_bf16 v[108:111], v[144:147], v[196:199], v[108:111]
	v_mfma_f32_16x16x32_bf16 v[104:107], v[136:139], v[208:211], v[104:107]
	v_mfma_f32_16x16x32_bf16 v[100:103], v[144:147], v[208:211], v[100:103]
	s_setprio 0
	s_setprio 1
	v_mfma_f32_16x16x32_bf16 v[62:65], v[148:151], v[164:167], v[62:65]
	v_mfma_f32_16x16x32_bf16 v[58:61], v[156:159], v[164:167], v[58:61]
	v_mfma_f32_16x16x32_bf16 v[54:57], v[148:151], v[182:185], v[54:57]
	v_mfma_f32_16x16x32_bf16 v[50:53], v[156:159], v[182:185], v[50:53]
	v_mfma_f32_16x16x32_bf16 v[46:49], v[148:151], v[192:195], v[46:49]
	v_mfma_f32_16x16x32_bf16 v[42:45], v[156:159], v[192:195], v[42:45]
	v_mfma_f32_16x16x32_bf16 v[38:41], v[148:151], v[204:207], v[38:41]
	v_mfma_f32_16x16x32_bf16 v[34:37], v[156:159], v[204:207], v[34:37]
	v_mfma_f32_16x16x32_bf16 v[62:65], v[152:155], v[178:181], v[62:65]
	v_mfma_f32_16x16x32_bf16 v[58:61], v[160:163], v[178:181], v[58:61]
	v_mfma_f32_16x16x32_bf16 v[54:57], v[152:155], v[188:191], v[54:57]
	v_mfma_f32_16x16x32_bf16 v[50:53], v[160:163], v[188:191], v[50:53]
	v_mfma_f32_16x16x32_bf16 v[46:49], v[152:155], v[196:199], v[46:49]
	v_mfma_f32_16x16x32_bf16 v[42:45], v[160:163], v[196:199], v[42:45]
	v_mfma_f32_16x16x32_bf16 v[38:41], v[152:155], v[208:211], v[38:41]
	v_mfma_f32_16x16x32_bf16 v[34:37], v[160:163], v[208:211], v[34:37]
	s_setprio 0
	s_barrier
	s_add_i32 s48, s58, s2
	v_lshl_add_u64 v[214:215], s[52:53], 0, v[98:99]
	s_mov_b32 m0, s48
	ds_read_b128 v[164:167], v187 offset:16384
	ds_read_b128 v[178:181], v187 offset:17408
	ds_read_b128 v[182:185], v187 offset:18432
	ds_read_b128 v[188:191], v187 offset:19456
	ds_read_b128 v[192:195], v187 offset:20480
	ds_read_b128 v[196:199], v187 offset:21504
	ds_read_b128 v[204:207], v187 offset:22528
	ds_read_b128 v[208:211], v187 offset:23552
	global_load_lds_dwordx4 v[214:215], off
	s_add_i32 m0, s48, 0x2000
	s_add_u32 s48, s52, 0xb0000
	v_lshl_add_u64 v[216:217], s[52:53], 0, v[168:169]
	s_addc_u32 s49, s53, 0
	s_add_i32 s58, s59, s2
	global_load_lds_dwordx4 v[216:217], off
	v_lshl_add_u64 v[218:219], s[48:49], 0, v[98:99]
	s_mov_b32 m0, s58
	v_lshl_add_u64 v[220:221], s[54:55], 0, v[170:171]
	global_load_lds_dwordx4 v[218:219], off
	v_lshl_add_u64 v[218:219], s[48:49], 0, v[168:169]
	s_add_i32 m0, s58, 0x2000
	s_nop 0
	global_load_lds_dwordx4 v[218:219], off
	v_lshl_add_u64 v[218:219], s[54:55], 0, v[172:173]
	s_mov_b32 m0, s4
	s_nop 0
	global_load_lds_dwordx4 v[218:219], off
	s_mov_b32 m0, s7
	s_nop 0
	global_load_lds_dwordx4 v[220:221], off
	s_waitcnt vmcnt(8)
	s_waitcnt lgkmcnt(0)
	s_setprio 1
	s_barrier
	v_mfma_f32_16x16x32_bf16 v[94:97], v[132:135], v[164:167], v[94:97]
	v_mfma_f32_16x16x32_bf16 v[90:93], v[140:143], v[164:167], v[90:93]
	v_mfma_f32_16x16x32_bf16 v[86:89], v[132:135], v[182:185], v[86:89]
	v_mfma_f32_16x16x32_bf16 v[82:85], v[140:143], v[182:185], v[82:85]
	v_mfma_f32_16x16x32_bf16 v[78:81], v[132:135], v[192:195], v[78:81]
	v_mfma_f32_16x16x32_bf16 v[74:77], v[140:143], v[192:195], v[74:77]
	v_mfma_f32_16x16x32_bf16 v[70:73], v[132:135], v[204:207], v[70:73]
	v_mfma_f32_16x16x32_bf16 v[66:69], v[140:143], v[204:207], v[66:69]
	v_mfma_f32_16x16x32_bf16 v[94:97], v[136:139], v[178:181], v[94:97]
	v_mfma_f32_16x16x32_bf16 v[90:93], v[144:147], v[178:181], v[90:93]
	v_mfma_f32_16x16x32_bf16 v[86:89], v[136:139], v[188:191], v[86:89]
	v_mfma_f32_16x16x32_bf16 v[82:85], v[144:147], v[188:191], v[82:85]
	v_mfma_f32_16x16x32_bf16 v[78:81], v[136:139], v[196:199], v[78:81]
	v_mfma_f32_16x16x32_bf16 v[74:77], v[144:147], v[196:199], v[74:77]
	v_mfma_f32_16x16x32_bf16 v[70:73], v[136:139], v[208:211], v[70:73]
	v_mfma_f32_16x16x32_bf16 v[66:69], v[144:147], v[208:211], v[66:69]
	s_setprio 0
	s_setprio 1
	v_mfma_f32_16x16x32_bf16 v[30:33], v[148:151], v[164:167], v[30:33]
	v_mfma_f32_16x16x32_bf16 v[26:29], v[156:159], v[164:167], v[26:29]
	v_mfma_f32_16x16x32_bf16 v[22:25], v[148:151], v[182:185], v[22:25]
	v_mfma_f32_16x16x32_bf16 v[18:21], v[156:159], v[182:185], v[18:21]
	v_mfma_f32_16x16x32_bf16 v[14:17], v[148:151], v[192:195], v[14:17]
	v_mfma_f32_16x16x32_bf16 v[10:13], v[156:159], v[192:195], v[10:13]
	v_mfma_f32_16x16x32_bf16 v[6:9], v[148:151], v[204:207], v[6:9]
	v_mfma_f32_16x16x32_bf16 v[2:5], v[156:159], v[204:207], v[2:5]
	v_mfma_f32_16x16x32_bf16 v[30:33], v[152:155], v[178:181], v[30:33]
	v_mfma_f32_16x16x32_bf16 v[26:29], v[160:163], v[178:181], v[26:29]
	v_mfma_f32_16x16x32_bf16 v[22:25], v[152:155], v[188:191], v[22:25]
	v_mfma_f32_16x16x32_bf16 v[18:21], v[160:163], v[188:191], v[18:21]
	v_mfma_f32_16x16x32_bf16 v[14:17], v[152:155], v[196:199], v[14:17]
	v_mfma_f32_16x16x32_bf16 v[10:13], v[160:163], v[196:199], v[10:13]
	v_mfma_f32_16x16x32_bf16 v[6:9], v[152:155], v[208:211], v[6:9]
	v_mfma_f32_16x16x32_bf16 v[2:5], v[160:163], v[208:211], v[2:5]
	s_setprio 0
	s_barrier
	s_add_i32 s58, 0, 0x18000
	s_add_i32 s59, 0, 0x1c000
	v_add_u32_e32 v144, s58, v186
	v_add_u32_e32 v160, s59, v186
	ds_read_b128 v[132:135], v144
	ds_read_b128 v[136:139], v144 offset:1024
	ds_read_b128 v[140:143], v144 offset:2048
	ds_read_b128 v[144:147], v144 offset:3072
	ds_read_b128 v[148:151], v160
	ds_read_b128 v[152:155], v160 offset:1024
	ds_read_b128 v[156:159], v160 offset:2048
	ds_read_b128 v[160:163], v160 offset:3072
	s_add_u32 s48, s54, 0xb0000
	s_addc_u32 s49, s55, 0
	s_mov_b32 m0, s8
	v_lshl_add_u64 v[222:223], s[48:49], 0, v[172:173]
	ds_read_b128 v[164:167], v187 offset:32768
	ds_read_b128 v[178:181], v187 offset:33792
	ds_read_b128 v[182:185], v187 offset:34816
	ds_read_b128 v[188:191], v187 offset:35840
	ds_read_b128 v[192:195], v187 offset:36864
	ds_read_b128 v[196:199], v187 offset:37888
	ds_read_b128 v[204:207], v187 offset:38912
	ds_read_b128 v[208:211], v187 offset:39936
	global_load_lds_dwordx4 v[222:223], off
	v_lshl_add_u64 v[222:223], s[48:49], 0, v[170:171]
	s_mov_b32 m0, s9
	s_nop 0
	global_load_lds_dwordx4 v[222:223], off
	s_waitcnt vmcnt(8)
	s_waitcnt lgkmcnt(0)
	s_setprio 1
	s_barrier
	v_mfma_f32_16x16x32_bf16 v[128:131], v[132:135], v[164:167], v[128:131]
	v_mfma_f32_16x16x32_bf16 v[124:127], v[140:143], v[164:167], v[124:127]
	v_mfma_f32_16x16x32_bf16 v[120:123], v[132:135], v[182:185], v[120:123]
	v_mfma_f32_16x16x32_bf16 v[116:119], v[140:143], v[182:185], v[116:119]
	v_mfma_f32_16x16x32_bf16 v[112:115], v[132:135], v[192:195], v[112:115]
	v_mfma_f32_16x16x32_bf16 v[108:111], v[140:143], v[192:195], v[108:111]
	v_mfma_f32_16x16x32_bf16 v[104:107], v[132:135], v[204:207], v[104:107]
	v_mfma_f32_16x16x32_bf16 v[100:103], v[140:143], v[204:207], v[100:103]
	v_mfma_f32_16x16x32_bf16 v[128:131], v[136:139], v[178:181], v[128:131]
	v_mfma_f32_16x16x32_bf16 v[124:127], v[144:147], v[178:181], v[124:127]
	v_mfma_f32_16x16x32_bf16 v[120:123], v[136:139], v[188:191], v[120:123]
	v_mfma_f32_16x16x32_bf16 v[116:119], v[144:147], v[188:191], v[116:119]
	v_mfma_f32_16x16x32_bf16 v[112:115], v[136:139], v[196:199], v[112:115]
	v_mfma_f32_16x16x32_bf16 v[108:111], v[144:147], v[196:199], v[108:111]
	v_mfma_f32_16x16x32_bf16 v[104:107], v[136:139], v[208:211], v[104:107]
	v_mfma_f32_16x16x32_bf16 v[100:103], v[144:147], v[208:211], v[100:103]
	s_setprio 0
	s_setprio 1
	v_mfma_f32_16x16x32_bf16 v[62:65], v[148:151], v[164:167], v[62:65]
	v_mfma_f32_16x16x32_bf16 v[58:61], v[156:159], v[164:167], v[58:61]
	v_mfma_f32_16x16x32_bf16 v[54:57], v[148:151], v[182:185], v[54:57]
	v_mfma_f32_16x16x32_bf16 v[50:53], v[156:159], v[182:185], v[50:53]
	v_mfma_f32_16x16x32_bf16 v[46:49], v[148:151], v[192:195], v[46:49]
	v_mfma_f32_16x16x32_bf16 v[42:45], v[156:159], v[192:195], v[42:45]
	v_mfma_f32_16x16x32_bf16 v[38:41], v[148:151], v[204:207], v[38:41]
	v_mfma_f32_16x16x32_bf16 v[34:37], v[156:159], v[204:207], v[34:37]
	v_mfma_f32_16x16x32_bf16 v[62:65], v[152:155], v[178:181], v[62:65]
	v_mfma_f32_16x16x32_bf16 v[58:61], v[160:163], v[178:181], v[58:61]
	v_mfma_f32_16x16x32_bf16 v[54:57], v[152:155], v[188:191], v[54:57]
	v_mfma_f32_16x16x32_bf16 v[50:53], v[160:163], v[188:191], v[50:53]
	v_mfma_f32_16x16x32_bf16 v[46:49], v[152:155], v[196:199], v[46:49]
	v_mfma_f32_16x16x32_bf16 v[42:45], v[160:163], v[196:199], v[42:45]
	v_mfma_f32_16x16x32_bf16 v[38:41], v[152:155], v[208:211], v[38:41]
	v_mfma_f32_16x16x32_bf16 v[34:37], v[160:163], v[208:211], v[34:37]
	s_setprio 0
	s_barrier
	s_add_i32 s48, s58, s2
	v_lshl_add_u64 v[214:215], v[214:215], 0, s[28:29]
	s_mov_b32 m0, s48
	ds_read_b128 v[164:167], v187 offset:49152
	ds_read_b128 v[178:181], v187 offset:50176
	ds_read_b128 v[182:185], v187 offset:51200
	ds_read_b128 v[188:191], v187 offset:52224
	ds_read_b128 v[192:195], v187 offset:53248
	ds_read_b128 v[196:199], v187 offset:54272
	ds_read_b128 v[204:207], v187 offset:55296
	ds_read_b128 v[208:211], v187 offset:56320
	global_load_lds_dwordx4 v[214:215], off
	s_add_i32 m0, s48, 0x2000
	s_add_u32 s48, s52, 0xb0080
	v_lshl_add_u64 v[214:215], v[216:217], 0, s[28:29]
	s_addc_u32 s49, s53, 0
	s_add_i32 s52, s59, s2
	global_load_lds_dwordx4 v[214:215], off
	v_lshl_add_u64 v[214:215], s[48:49], 0, v[98:99]
	s_mov_b32 m0, s52
	s_nop 0
	global_load_lds_dwordx4 v[214:215], off
	v_lshl_add_u64 v[214:215], s[48:49], 0, v[168:169]
	s_add_i32 m0, s52, 0x2000
	s_nop 0
	global_load_lds_dwordx4 v[214:215], off
	v_lshl_add_u64 v[214:215], v[218:219], 0, s[28:29]
	s_mov_b32 m0, s12
	s_nop 0
	global_load_lds_dwordx4 v[214:215], off
	v_lshl_add_u64 v[214:215], v[220:221], 0, s[28:29]
	s_mov_b32 m0, s13
	s_nop 0
	global_load_lds_dwordx4 v[214:215], off
	s_waitcnt vmcnt(8)
	s_waitcnt lgkmcnt(0)
	s_setprio 1
	s_barrier
	v_mfma_f32_16x16x32_bf16 v[94:97], v[132:135], v[164:167], v[94:97]
	v_mfma_f32_16x16x32_bf16 v[90:93], v[140:143], v[164:167], v[90:93]
	v_mfma_f32_16x16x32_bf16 v[86:89], v[132:135], v[182:185], v[86:89]
	v_mfma_f32_16x16x32_bf16 v[82:85], v[140:143], v[182:185], v[82:85]
	v_mfma_f32_16x16x32_bf16 v[78:81], v[132:135], v[192:195], v[78:81]
	v_mfma_f32_16x16x32_bf16 v[74:77], v[140:143], v[192:195], v[74:77]
	v_mfma_f32_16x16x32_bf16 v[70:73], v[132:135], v[204:207], v[70:73]
	v_mfma_f32_16x16x32_bf16 v[66:69], v[140:143], v[204:207], v[66:69]
	v_mfma_f32_16x16x32_bf16 v[94:97], v[136:139], v[178:181], v[94:97]
	v_mfma_f32_16x16x32_bf16 v[90:93], v[144:147], v[178:181], v[90:93]
	v_mfma_f32_16x16x32_bf16 v[86:89], v[136:139], v[188:191], v[86:89]
	v_mfma_f32_16x16x32_bf16 v[82:85], v[144:147], v[188:191], v[82:85]
	v_mfma_f32_16x16x32_bf16 v[78:81], v[136:139], v[196:199], v[78:81]
	v_mfma_f32_16x16x32_bf16 v[74:77], v[144:147], v[196:199], v[74:77]
	v_mfma_f32_16x16x32_bf16 v[70:73], v[136:139], v[208:211], v[70:73]
	v_mfma_f32_16x16x32_bf16 v[66:69], v[144:147], v[208:211], v[66:69]
	s_setprio 0
	s_setprio 1
	v_mfma_f32_16x16x32_bf16 v[30:33], v[148:151], v[164:167], v[30:33]
	v_mfma_f32_16x16x32_bf16 v[26:29], v[156:159], v[164:167], v[26:29]
	v_mfma_f32_16x16x32_bf16 v[22:25], v[148:151], v[182:185], v[22:25]
	v_mfma_f32_16x16x32_bf16 v[18:21], v[156:159], v[182:185], v[18:21]
	v_mfma_f32_16x16x32_bf16 v[14:17], v[148:151], v[192:195], v[14:17]
	v_mfma_f32_16x16x32_bf16 v[10:13], v[156:159], v[192:195], v[10:13]
	v_mfma_f32_16x16x32_bf16 v[6:9], v[148:151], v[204:207], v[6:9]
	v_mfma_f32_16x16x32_bf16 v[2:5], v[156:159], v[204:207], v[2:5]
	v_mfma_f32_16x16x32_bf16 v[30:33], v[152:155], v[178:181], v[30:33]
	v_mfma_f32_16x16x32_bf16 v[26:29], v[160:163], v[178:181], v[26:29]
	v_mfma_f32_16x16x32_bf16 v[22:25], v[152:155], v[188:191], v[22:25]
	v_mfma_f32_16x16x32_bf16 v[18:21], v[160:163], v[188:191], v[18:21]
	v_mfma_f32_16x16x32_bf16 v[14:17], v[152:155], v[196:199], v[14:17]
	v_mfma_f32_16x16x32_bf16 v[10:13], v[160:163], v[196:199], v[10:13]
	v_mfma_f32_16x16x32_bf16 v[6:9], v[152:155], v[208:211], v[6:9]
	v_mfma_f32_16x16x32_bf16 v[2:5], v[160:163], v[208:211], v[2:5]
	s_setprio 0
	s_barrier
	s_add_i32 s57, s57, 2
	s_add_u32 s33, s33, 0x100
	s_addc_u32 s56, s56, 0
	s_cmp_gt_u32 s57, 41
	s_mov_b64 s[48:49], s[50:51]
	s_cbranch_scc0 .LBB0_1529
	s_and_b64 vcc, exec, s[44:45]
	s_cbranch_vccz .LBB0_1532
	s_barrier

.LBB0_1553:
	s_add_i32 s63, s54, 2
	s_add_u32 s52, s50, 0x100
	s_addc_u32 s53, s51, 0
	s_add_i32 s64, 0, 0x10000
	s_cmp_eq_u32 s60, s54
	s_cselect_b32 s57, s45, s53
	s_cselect_b32 s56, s44, s52
	s_cselect_b32 s55, s47, s62
	s_cselect_b32 s54, s46, s61
	s_add_i32 s65, 0, 0x14000
	v_add_u32_e32 v144, s64, v198
	v_add_u32_e32 v160, s65, v198
	s_waitcnt lgkmcnt(0)
	ds_read_b128 v[132:135], v144
	ds_read_b128 v[136:139], v144 offset:1024
	ds_read_b128 v[140:143], v144 offset:2048
	ds_read_b128 v[144:147], v144 offset:3072
	ds_read_b128 v[148:151], v160
	ds_read_b128 v[152:155], v160 offset:1024
	ds_read_b128 v[156:159], v160 offset:2048
	ds_read_b128 v[160:163], v160 offset:3072
	v_lshl_add_u64 v[214:215], s[50:51], 0, v[178:179]
	s_add_i32 m0, s4, 0xc000
	ds_read_b128 v[164:167], v199
	ds_read_b128 v[168:171], v199 offset:1024
	ds_read_b128 v[182:185], v199 offset:2048
	ds_read_b128 v[186:189], v199 offset:3072
	ds_read_b128 v[190:193], v199 offset:4096
	ds_read_b128 v[194:197], v199 offset:5120
	ds_read_b128 v[204:207], v199 offset:6144
	ds_read_b128 v[208:211], v199 offset:7168
	global_load_lds_dwordx4 v[214:215], off
	v_lshl_add_u64 v[214:215], s[50:51], 0, v[180:181]
	s_add_i32 m0, s4, 0xe000
	s_nop 0
	global_load_lds_dwordx4 v[214:215], off
	s_waitcnt vmcnt(8)
	s_waitcnt lgkmcnt(0)
	s_setprio 1
	s_barrier
	v_mfma_f32_16x16x32_bf16 v[128:131], v[132:135], v[164:167], v[128:131]
	v_mfma_f32_16x16x32_bf16 v[124:127], v[140:143], v[164:167], v[124:127]
	v_mfma_f32_16x16x32_bf16 v[120:123], v[132:135], v[182:185], v[120:123]
	v_mfma_f32_16x16x32_bf16 v[116:119], v[140:143], v[182:185], v[116:119]
	v_mfma_f32_16x16x32_bf16 v[104:107], v[132:135], v[190:193], v[104:107]
	v_mfma_f32_16x16x32_bf16 v[100:103], v[140:143], v[190:193], v[100:103]
	v_mfma_f32_16x16x32_bf16 v[86:89], v[132:135], v[204:207], v[86:89]
	v_mfma_f32_16x16x32_bf16 v[82:85], v[140:143], v[204:207], v[82:85]
	v_mfma_f32_16x16x32_bf16 v[128:131], v[136:139], v[168:171], v[128:131]
	v_mfma_f32_16x16x32_bf16 v[124:127], v[144:147], v[168:171], v[124:127]
	v_mfma_f32_16x16x32_bf16 v[120:123], v[136:139], v[186:189], v[120:123]
	v_mfma_f32_16x16x32_bf16 v[116:119], v[144:147], v[186:189], v[116:119]
	v_mfma_f32_16x16x32_bf16 v[104:107], v[136:139], v[194:197], v[104:107]
	v_mfma_f32_16x16x32_bf16 v[100:103], v[144:147], v[194:197], v[100:103]
	v_mfma_f32_16x16x32_bf16 v[86:89], v[136:139], v[208:211], v[86:89]
	v_mfma_f32_16x16x32_bf16 v[82:85], v[144:147], v[208:211], v[82:85]
	s_setprio 0
	s_setprio 1
	v_mfma_f32_16x16x32_bf16 v[112:115], v[148:151], v[164:167], v[112:115]
	v_mfma_f32_16x16x32_bf16 v[108:111], v[156:159], v[164:167], v[108:111]
	v_mfma_f32_16x16x32_bf16 v[94:97], v[148:151], v[182:185], v[94:97]
	v_mfma_f32_16x16x32_bf16 v[90:93], v[156:159], v[182:185], v[90:93]
	v_mfma_f32_16x16x32_bf16 v[78:81], v[148:151], v[190:193], v[78:81]
	v_mfma_f32_16x16x32_bf16 v[74:77], v[156:159], v[190:193], v[74:77]
	v_mfma_f32_16x16x32_bf16 v[70:73], v[148:151], v[204:207], v[70:73]
	v_mfma_f32_16x16x32_bf16 v[66:69], v[156:159], v[204:207], v[66:69]
	v_mfma_f32_16x16x32_bf16 v[112:115], v[152:155], v[168:171], v[112:115]
	v_mfma_f32_16x16x32_bf16 v[108:111], v[160:163], v[168:171], v[108:111]
	v_mfma_f32_16x16x32_bf16 v[94:97], v[152:155], v[186:189], v[94:97]
	v_mfma_f32_16x16x32_bf16 v[90:93], v[160:163], v[186:189], v[90:93]
	v_mfma_f32_16x16x32_bf16 v[78:81], v[152:155], v[194:197], v[78:81]
	v_mfma_f32_16x16x32_bf16 v[74:77], v[160:163], v[194:197], v[74:77]
	v_mfma_f32_16x16x32_bf16 v[70:73], v[152:155], v[208:211], v[70:73]
	v_mfma_f32_16x16x32_bf16 v[66:69], v[160:163], v[208:211], v[66:69]
	s_setprio 0
	s_barrier
	s_add_i32 s50, s64, s2
	v_lshl_add_u64 v[214:215], s[54:55], 0, v[98:99]
	s_mov_b32 m0, s50
	ds_read_b128 v[164:167], v199 offset:16384
	ds_read_b128 v[168:171], v199 offset:17408
	ds_read_b128 v[182:185], v199 offset:18432
	ds_read_b128 v[186:189], v199 offset:19456
	ds_read_b128 v[190:193], v199 offset:20480
	ds_read_b128 v[194:197], v199 offset:21504
	ds_read_b128 v[204:207], v199 offset:22528
	ds_read_b128 v[208:211], v199 offset:23552
	global_load_lds_dwordx4 v[214:215], off
	s_add_i32 m0, s50, 0x2000
	s_add_u32 s50, s54, 0xb0000
	v_lshl_add_u64 v[216:217], s[54:55], 0, v[172:173]
	s_addc_u32 s51, s55, 0
	s_add_i32 s64, s65, s2
	global_load_lds_dwordx4 v[216:217], off
	v_lshl_add_u64 v[218:219], s[50:51], 0, v[98:99]
	s_mov_b32 m0, s64
	v_lshl_add_u64 v[220:221], s[56:57], 0, v[174:175]
	global_load_lds_dwordx4 v[218:219], off
	v_lshl_add_u64 v[218:219], s[50:51], 0, v[172:173]
	s_add_i32 m0, s64, 0x2000
	s_nop 0
	global_load_lds_dwordx4 v[218:219], off
	v_lshl_add_u64 v[218:219], s[56:57], 0, v[176:177]
	s_mov_b32 m0, s4
	s_nop 0
	global_load_lds_dwordx4 v[218:219], off
	s_mov_b32 m0, s7
	s_nop 0
	global_load_lds_dwordx4 v[220:221], off
	s_waitcnt vmcnt(8)
	s_waitcnt lgkmcnt(0)
	s_setprio 1
	s_barrier
	v_mfma_f32_16x16x32_bf16 v[62:65], v[132:135], v[164:167], v[62:65]
	v_mfma_f32_16x16x32_bf16 v[58:61], v[140:143], v[164:167], v[58:61]
	v_mfma_f32_16x16x32_bf16 v[54:57], v[132:135], v[182:185], v[54:57]
	v_mfma_f32_16x16x32_bf16 v[50:53], v[140:143], v[182:185], v[50:53]
	v_mfma_f32_16x16x32_bf16 v[38:41], v[132:135], v[190:193], v[38:41]
	v_mfma_f32_16x16x32_bf16 v[34:37], v[140:143], v[190:193], v[34:37]
	v_mfma_f32_16x16x32_bf16 v[22:25], v[132:135], v[204:207], v[22:25]
	v_mfma_f32_16x16x32_bf16 v[18:21], v[140:143], v[204:207], v[18:21]
	v_mfma_f32_16x16x32_bf16 v[62:65], v[136:139], v[168:171], v[62:65]
	v_mfma_f32_16x16x32_bf16 v[58:61], v[144:147], v[168:171], v[58:61]
	v_mfma_f32_16x16x32_bf16 v[54:57], v[136:139], v[186:189], v[54:57]
	v_mfma_f32_16x16x32_bf16 v[50:53], v[144:147], v[186:189], v[50:53]
	v_mfma_f32_16x16x32_bf16 v[38:41], v[136:139], v[194:197], v[38:41]
	v_mfma_f32_16x16x32_bf16 v[34:37], v[144:147], v[194:197], v[34:37]
	v_mfma_f32_16x16x32_bf16 v[22:25], v[136:139], v[208:211], v[22:25]
	v_mfma_f32_16x16x32_bf16 v[18:21], v[144:147], v[208:211], v[18:21]
	s_setprio 0
	s_setprio 1
	v_mfma_f32_16x16x32_bf16 v[46:49], v[148:151], v[164:167], v[46:49]
	v_mfma_f32_16x16x32_bf16 v[42:45], v[156:159], v[164:167], v[42:45]
	v_mfma_f32_16x16x32_bf16 v[30:33], v[148:151], v[182:185], v[30:33]
	v_mfma_f32_16x16x32_bf16 v[26:29], v[156:159], v[182:185], v[26:29]
	v_mfma_f32_16x16x32_bf16 v[14:17], v[148:151], v[190:193], v[14:17]
	v_mfma_f32_16x16x32_bf16 v[10:13], v[156:159], v[190:193], v[10:13]
	v_mfma_f32_16x16x32_bf16 v[6:9], v[148:151], v[204:207], v[6:9]
	v_mfma_f32_16x16x32_bf16 v[2:5], v[156:159], v[204:207], v[2:5]
	v_mfma_f32_16x16x32_bf16 v[46:49], v[152:155], v[168:171], v[46:49]
	v_mfma_f32_16x16x32_bf16 v[42:45], v[160:163], v[168:171], v[42:45]
	v_mfma_f32_16x16x32_bf16 v[30:33], v[152:155], v[186:189], v[30:33]
	v_mfma_f32_16x16x32_bf16 v[26:29], v[160:163], v[186:189], v[26:29]
	v_mfma_f32_16x16x32_bf16 v[14:17], v[152:155], v[194:197], v[14:17]
	v_mfma_f32_16x16x32_bf16 v[10:13], v[160:163], v[194:197], v[10:13]
	v_mfma_f32_16x16x32_bf16 v[6:9], v[152:155], v[208:211], v[6:9]
	v_mfma_f32_16x16x32_bf16 v[2:5], v[160:163], v[208:211], v[2:5]
	s_setprio 0
	s_barrier
	s_add_i32 s64, 0, 0x18000
	s_add_i32 s65, 0, 0x1c000
	v_add_u32_e32 v144, s64, v198
	v_add_u32_e32 v160, s65, v198
	ds_read_b128 v[132:135], v144
	ds_read_b128 v[136:139], v144 offset:1024
	ds_read_b128 v[140:143], v144 offset:2048
	ds_read_b128 v[144:147], v144 offset:3072
	ds_read_b128 v[148:151], v160
	ds_read_b128 v[152:155], v160 offset:1024
	ds_read_b128 v[156:159], v160 offset:2048
	ds_read_b128 v[160:163], v160 offset:3072
	s_add_u32 s50, s56, 0xb0000
	s_addc_u32 s51, s57, 0
	s_mov_b32 m0, s8
	v_lshl_add_u64 v[222:223], s[50:51], 0, v[176:177]
	ds_read_b128 v[164:167], v199 offset:32768
	ds_read_b128 v[168:171], v199 offset:33792
	ds_read_b128 v[182:185], v199 offset:34816
	ds_read_b128 v[186:189], v199 offset:35840
	ds_read_b128 v[190:193], v199 offset:36864
	ds_read_b128 v[194:197], v199 offset:37888
	ds_read_b128 v[204:207], v199 offset:38912
	ds_read_b128 v[208:211], v199 offset:39936
	global_load_lds_dwordx4 v[222:223], off
	v_lshl_add_u64 v[222:223], s[50:51], 0, v[174:175]
	s_mov_b32 m0, s9
	s_nop 0
	global_load_lds_dwordx4 v[222:223], off
	s_waitcnt vmcnt(8)
	s_waitcnt lgkmcnt(0)
	s_setprio 1
	s_barrier
	v_mfma_f32_16x16x32_bf16 v[128:131], v[132:135], v[164:167], v[128:131]
	v_mfma_f32_16x16x32_bf16 v[124:127], v[140:143], v[164:167], v[124:127]
	v_mfma_f32_16x16x32_bf16 v[120:123], v[132:135], v[182:185], v[120:123]
	v_mfma_f32_16x16x32_bf16 v[116:119], v[140:143], v[182:185], v[116:119]
	v_mfma_f32_16x16x32_bf16 v[104:107], v[132:135], v[190:193], v[104:107]
	v_mfma_f32_16x16x32_bf16 v[100:103], v[140:143], v[190:193], v[100:103]
	v_mfma_f32_16x16x32_bf16 v[86:89], v[132:135], v[204:207], v[86:89]
	v_mfma_f32_16x16x32_bf16 v[82:85], v[140:143], v[204:207], v[82:85]
	v_mfma_f32_16x16x32_bf16 v[128:131], v[136:139], v[168:171], v[128:131]
	v_mfma_f32_16x16x32_bf16 v[124:127], v[144:147], v[168:171], v[124:127]
	v_mfma_f32_16x16x32_bf16 v[120:123], v[136:139], v[186:189], v[120:123]
	v_mfma_f32_16x16x32_bf16 v[116:119], v[144:147], v[186:189], v[116:119]
	v_mfma_f32_16x16x32_bf16 v[104:107], v[136:139], v[194:197], v[104:107]
	v_mfma_f32_16x16x32_bf16 v[100:103], v[144:147], v[194:197], v[100:103]
	v_mfma_f32_16x16x32_bf16 v[86:89], v[136:139], v[208:211], v[86:89]
	v_mfma_f32_16x16x32_bf16 v[82:85], v[144:147], v[208:211], v[82:85]
	s_setprio 0
	s_setprio 1
	v_mfma_f32_16x16x32_bf16 v[112:115], v[148:151], v[164:167], v[112:115]
	v_mfma_f32_16x16x32_bf16 v[108:111], v[156:159], v[164:167], v[108:111]
	v_mfma_f32_16x16x32_bf16 v[94:97], v[148:151], v[182:185], v[94:97]
	v_mfma_f32_16x16x32_bf16 v[90:93], v[156:159], v[182:185], v[90:93]
	v_mfma_f32_16x16x32_bf16 v[78:81], v[148:151], v[190:193], v[78:81]
	v_mfma_f32_16x16x32_bf16 v[74:77], v[156:159], v[190:193], v[74:77]
	v_mfma_f32_16x16x32_bf16 v[70:73], v[148:151], v[204:207], v[70:73]
	v_mfma_f32_16x16x32_bf16 v[66:69], v[156:159], v[204:207], v[66:69]
	v_mfma_f32_16x16x32_bf16 v[112:115], v[152:155], v[168:171], v[112:115]
	v_mfma_f32_16x16x32_bf16 v[108:111], v[160:163], v[168:171], v[108:111]
	v_mfma_f32_16x16x32_bf16 v[94:97], v[152:155], v[186:189], v[94:97]
	v_mfma_f32_16x16x32_bf16 v[90:93], v[160:163], v[186:189], v[90:93]
	v_mfma_f32_16x16x32_bf16 v[78:81], v[152:155], v[194:197], v[78:81]
	v_mfma_f32_16x16x32_bf16 v[74:77], v[160:163], v[194:197], v[74:77]
	v_mfma_f32_16x16x32_bf16 v[70:73], v[152:155], v[208:211], v[70:73]
	v_mfma_f32_16x16x32_bf16 v[66:69], v[160:163], v[208:211], v[66:69]
	s_setprio 0
	s_barrier
	s_add_i32 s50, s64, s2
	v_lshl_add_u64 v[214:215], v[214:215], 0, s[28:29]
	s_mov_b32 m0, s50
	ds_read_b128 v[164:167], v199 offset:49152
	ds_read_b128 v[168:171], v199 offset:50176
	ds_read_b128 v[182:185], v199 offset:51200
	ds_read_b128 v[186:189], v199 offset:52224
	ds_read_b128 v[190:193], v199 offset:53248
	ds_read_b128 v[194:197], v199 offset:54272
	ds_read_b128 v[204:207], v199 offset:55296
	ds_read_b128 v[208:211], v199 offset:56320
	global_load_lds_dwordx4 v[214:215], off
	s_add_i32 m0, s50, 0x2000
	s_add_u32 s50, s54, 0xb0080
	v_lshl_add_u64 v[214:215], v[216:217], 0, s[28:29]
	s_addc_u32 s51, s55, 0
	s_add_i32 s54, s65, s2
	global_load_lds_dwordx4 v[214:215], off
	v_lshl_add_u64 v[214:215], s[50:51], 0, v[98:99]
	s_mov_b32 m0, s54
	s_nop 0
	global_load_lds_dwordx4 v[214:215], off
	v_lshl_add_u64 v[214:215], s[50:51], 0, v[172:173]
	s_add_i32 m0, s54, 0x2000
	s_nop 0
	global_load_lds_dwordx4 v[214:215], off
	v_lshl_add_u64 v[214:215], v[218:219], 0, s[28:29]
	s_mov_b32 m0, s12
	s_nop 0
	global_load_lds_dwordx4 v[214:215], off
	v_lshl_add_u64 v[214:215], v[220:221], 0, s[28:29]
	s_mov_b32 m0, s13
	s_nop 0
	global_load_lds_dwordx4 v[214:215], off
	s_waitcnt vmcnt(8)
	s_waitcnt lgkmcnt(0)
	s_setprio 1
	s_barrier
	v_mfma_f32_16x16x32_bf16 v[62:65], v[132:135], v[164:167], v[62:65]
	v_mfma_f32_16x16x32_bf16 v[58:61], v[140:143], v[164:167], v[58:61]
	v_mfma_f32_16x16x32_bf16 v[54:57], v[132:135], v[182:185], v[54:57]
	v_mfma_f32_16x16x32_bf16 v[50:53], v[140:143], v[182:185], v[50:53]
	v_mfma_f32_16x16x32_bf16 v[38:41], v[132:135], v[190:193], v[38:41]
	v_mfma_f32_16x16x32_bf16 v[34:37], v[140:143], v[190:193], v[34:37]
	v_mfma_f32_16x16x32_bf16 v[22:25], v[132:135], v[204:207], v[22:25]
	v_mfma_f32_16x16x32_bf16 v[18:21], v[140:143], v[204:207], v[18:21]
	v_mfma_f32_16x16x32_bf16 v[62:65], v[136:139], v[168:171], v[62:65]
	v_mfma_f32_16x16x32_bf16 v[58:61], v[144:147], v[168:171], v[58:61]
	v_mfma_f32_16x16x32_bf16 v[54:57], v[136:139], v[186:189], v[54:57]
	v_mfma_f32_16x16x32_bf16 v[50:53], v[144:147], v[186:189], v[50:53]
	v_mfma_f32_16x16x32_bf16 v[38:41], v[136:139], v[194:197], v[38:41]
	v_mfma_f32_16x16x32_bf16 v[34:37], v[144:147], v[194:197], v[34:37]
	v_mfma_f32_16x16x32_bf16 v[22:25], v[136:139], v[208:211], v[22:25]
	v_mfma_f32_16x16x32_bf16 v[18:21], v[144:147], v[208:211], v[18:21]
	s_setprio 0
	s_setprio 1
	v_mfma_f32_16x16x32_bf16 v[46:49], v[148:151], v[164:167], v[46:49]
	v_mfma_f32_16x16x32_bf16 v[42:45], v[156:159], v[164:167], v[42:45]
	v_mfma_f32_16x16x32_bf16 v[30:33], v[148:151], v[182:185], v[30:33]
	v_mfma_f32_16x16x32_bf16 v[26:29], v[156:159], v[182:185], v[26:29]
	v_mfma_f32_16x16x32_bf16 v[14:17], v[148:151], v[190:193], v[14:17]
	v_mfma_f32_16x16x32_bf16 v[10:13], v[156:159], v[190:193], v[10:13]
	v_mfma_f32_16x16x32_bf16 v[6:9], v[148:151], v[204:207], v[6:9]
	v_mfma_f32_16x16x32_bf16 v[2:5], v[156:159], v[204:207], v[2:5]
	v_mfma_f32_16x16x32_bf16 v[46:49], v[152:155], v[168:171], v[46:49]
	v_mfma_f32_16x16x32_bf16 v[42:45], v[160:163], v[168:171], v[42:45]
	v_mfma_f32_16x16x32_bf16 v[30:33], v[152:155], v[186:189], v[30:33]
	v_mfma_f32_16x16x32_bf16 v[26:29], v[160:163], v[186:189], v[26:29]
	v_mfma_f32_16x16x32_bf16 v[14:17], v[152:155], v[194:197], v[14:17]
	v_mfma_f32_16x16x32_bf16 v[10:13], v[160:163], v[194:197], v[10:13]
	v_mfma_f32_16x16x32_bf16 v[6:9], v[152:155], v[208:211], v[6:9]
	v_mfma_f32_16x16x32_bf16 v[2:5], v[160:163], v[208:211], v[2:5]
	s_setprio 0
	s_barrier
	s_add_u32 s61, s61, 0x100
	s_addc_u32 s62, s62, 0
	s_cmp_ge_i32 s63, s59
	s_mov_b64 s[50:51], s[52:53]
	s_mov_b32 s54, s63
	s_cbranch_scc0 .LBB0_1553
	s_and_b64 vcc, exec, s[42:43]
	s_cbranch_vccz .LBB0_1556
	s_barrier
